# v28
# speedup vs baseline: 1.0087x; 1.0035x over previous
.LBB0_171:
	s_or_b64 exec, exec, s[8:9]
	v_add_u32_e32 v136, s30, v44
	v_lshlrev_b32_e32 v44, 7, v38
	v_and_b32_e32 v45, 7, v38
	v_bitop3_b32 v38, v38, v1, 7 bitop3:0x6c
	v_lshl_or_b32 v38, v38, 4, v44
	v_add_u32_e32 v138, 0, v38
	v_xor_b32_e32 v38, v43, v1
	v_bitop3_b32 v1, v43, v1, 4 bitop3:0x36
	v_lshlrev_b32_e32 v144, 4, v38
	v_lshlrev_b32_e32 v146, 4, v1
	v_xor_b32_e32 v1, 16, v214
	v_add_u32_e32 v38, 64, v39
	v_cmp_lt_i32_e64 s[8:9], v1, v38
	s_lshr_b32 s30, s16, 6
	s_add_i32 s80, s30, -2
	v_cndmask_b32_e64 v1, v214, v1, s[8:9]
	v_lshlrev_b32_e32 v135, 2, v1
	v_xor_b32_e32 v1, 32, v214
	v_cmp_lt_i32_e64 s[8:9], v1, v38
	v_and_b32_e32 v46, 4, v42
	v_lshlrev_b32_e32 v42, 1, v42
	v_cndmask_b32_e64 v1, v214, v1, s[8:9]
	s_add_u32 s8, s20, s13
	s_addc_u32 s9, s21, 0
	v_lshl_add_u64 v[106:107], s[8:9], 0, v[36:37]
	s_and_b32 s8, s52, 15
	v_and_b32_e32 v42, 2, v42
	s_lshl_b32 s8, s8, 7
	v_or_b32_e32 v47, v42, v46
	s_add_u32 s8, s20, s8
	v_bitop3_b32 v42, v42, v45, v46 bitop3:0x36
	v_bitop3_b32 v45, v47, v45, 1 bitop3:0x36
	s_addc_u32 s9, s21, 0
	v_and_b32_e32 v40, 8, v40
	v_lshlrev_b32_e32 v42, 4, v42
	v_lshlrev_b32_e32 v45, 4, v45
	s_add_u32 s8, s8, s12
	v_or3_b32 v42, v42, v44, v40
	v_or3_b32 v40, v45, v44, v40
	s_addc_u32 s9, s9, 0
	v_mov_b32_e32 v46, v0
	v_mov_b32_e32 v47, v0
	v_mov_b32_e32 v48, v0
	v_mov_b32_e32 v49, v0
	v_add_u32_e32 v139, 0, v42
	v_add_u32_e32 v140, 0, v40
	v_lshlrev_b32_e32 v137, 2, v43
	v_lshl_add_u32 v142, v43, 4, 0
	v_lshlrev_b32_e32 v143, 7, v41
	v_or_b32_e32 v148, v136, v41
	v_lshlrev_b32_e32 v101, 2, v1
	v_lshl_add_u64 v[108:109], s[8:9], 0, v[34:35]
	v_mov_b32_e32 v1, v0
	v_mov_b64_e32 v[64:65], v[48:49]
	v_mov_b64_e32 v[42:43], v[46:47]
	v_mov_b64_e32 v[60:61], v[48:49]
	v_mov_b64_e32 v[38:39], v[46:47]
	v_mov_b64_e32 v[56:57], v[48:49]
	v_mov_b64_e32 v[34:35], v[46:47]
	v_mov_b64_e32 v[52:53], v[48:49]
	v_or_b32_e32 v141, 31, v136
	v_add_u32_e32 v145, 0, v144
	v_add_u32_e32 v147, 0, v146
	v_or_b32_e32 v149, 16, v148
	v_add_u32_e32 v150, 0, v143
	v_mov_b32_e32 v99, v0
	v_mov_b32_e32 v110, 0xff800000
	s_mov_b32 s65, 3
	s_movk_i32 s81, 0x7f
	s_xor_b64 s[12:13], vcc, -1
	v_mov_b64_e32 v[62:63], v[46:47]
	v_mov_b64_e32 v[44:45], v[48:49]
	v_mov_b64_e32 v[58:59], v[46:47]
	v_mov_b64_e32 v[40:41], v[48:49]
	v_mov_b64_e32 v[54:55], v[46:47]
	v_mov_b64_e32 v[36:37], v[48:49]
	v_mov_b64_e32 v[50:51], v[46:47]
	v_mov_b32_e32 v111, 0xff800000
	v_mov_b64_e32 v[104:105], v[0:1]
	ds_write_b128 v138, v[2:5] offset:8704
	ds_write_b64 v139, v[6:7] offset:25088
	ds_write_b64 v140, v[8:9] offset:25088
	s_waitcnt lgkmcnt(0)
	v_add_u32_e32 v186, v145, v143
	v_add_u32_e32 v187, v147, v143
	v_add_u32_e32 v188, v150, v144
	v_add_u32_e32 v189, v150, v146
	s_waitcnt vmcnt(0)
	s_barrier
	s_branch .LBB0_174

.LBB0_176:
	s_add_i32 s8, s81, 0xffffff81
	v_cmp_le_i32_e32 vcc, s8, v141
	s_and_b64 s[8:9], s[12:13], vcc
	s_and_saveexec_b64 s[16:17], s[8:9]
	s_cbranch_execz .LBB0_180
	ds_read_b128 v[66:69], v142
	ds_read_b128 v[70:73], v142 offset:64
	ds_read_b128 v[74:77], v142 offset:128
	ds_read_b128 v[78:81], v142 offset:192
	ds_read_b128 v[154:157], v186 offset:8704
	ds_read_b128 v[158:161], v186 offset:10752
	ds_read_b128 v[162:165], v186 offset:12800
	ds_read_b128 v[166:169], v186 offset:14848
	ds_read_b128 v[170:173], v187 offset:8704
	ds_read_b128 v[174:177], v187 offset:10752
	ds_read_b128 v[178:181], v187 offset:12800
	ds_read_b128 v[182:185], v187 offset:14848
	s_sub_i32 s8, s81, 64
	v_cmp_gt_i32_e32 vcc, s8, v136
	s_waitcnt lgkmcnt(7)
	v_mfma_f32_16x16x32_bf16 v[86:89], v[154:157], v[30:33], v[66:69]
	v_mfma_f32_16x16x32_bf16 v[66:69], v[154:157], v[26:29], v[66:69]
	s_waitcnt lgkmcnt(6)
	v_mfma_f32_16x16x32_bf16 v[90:93], v[158:161], v[30:33], v[70:73]
	v_mfma_f32_16x16x32_bf16 v[70:73], v[158:161], v[26:29], v[70:73]
	s_waitcnt lgkmcnt(5)
	v_mfma_f32_16x16x32_bf16 v[94:97], v[162:165], v[30:33], v[74:77]
	v_mfma_f32_16x16x32_bf16 v[112:115], v[162:165], v[26:29], v[74:77]
	s_waitcnt lgkmcnt(4)
	v_mfma_f32_16x16x32_bf16 v[116:119], v[166:169], v[30:33], v[78:81]
	v_mfma_f32_16x16x32_bf16 v[120:123], v[166:169], v[26:29], v[78:81]
	s_waitcnt lgkmcnt(3)
	v_mfma_f32_16x16x32_bf16 v[82:85], v[170:173], v[18:21], v[66:69]
	v_mfma_f32_16x16x32_bf16 v[74:77], v[170:173], v[22:25], v[86:89]
	s_waitcnt lgkmcnt(2)
	v_mfma_f32_16x16x32_bf16 v[90:93], v[174:177], v[22:25], v[90:93]
	v_mfma_f32_16x16x32_bf16 v[86:89], v[174:177], v[18:21], v[70:73]
	s_waitcnt lgkmcnt(1)
	v_mfma_f32_16x16x32_bf16 v[78:81], v[178:181], v[22:25], v[94:97]
	v_mfma_f32_16x16x32_bf16 v[66:69], v[178:181], v[18:21], v[112:115]
	s_waitcnt lgkmcnt(0)
	v_mfma_f32_16x16x32_bf16 v[94:97], v[182:185], v[22:25], v[116:119]
	v_mfma_f32_16x16x32_bf16 v[70:73], v[182:185], v[18:21], v[120:123]
	s_and_saveexec_b64 s[78:79], vcc
	s_cbranch_execz .LBB0_179
	v_add_u32_e32 v1, s81, v137
	v_add_u32_e32 v113, 0xffffff81, v1
	v_mov_b32_e32 v112, s41
	v_cmp_gt_i32_e32 vcc, v113, v148
	v_cmp_lt_i32_e64 s[8:9], v113, v148
	v_add_u32_e32 v114, 0xffffff83, v1
	v_cndmask_b32_e32 v112, v74, v112, vcc
	v_cndmask_b32_e64 v74, v112, v74, s[8:9]
	v_cndmask_b32_e64 v75, v221, v75, s[8:9]
	v_cmp_le_i32_e64 s[8:9], v114, v148
	v_add_u32_e32 v115, 0xffffff84, v1
	v_mov_b32_e32 v112, s41
	v_cndmask_b32_e64 v76, v221, v76, s[8:9]
	v_cmp_le_i32_e64 s[8:9], v115, v148
	v_add_u32_e32 v116, 0xffffffa4, v1
	s_nop 0
	v_cndmask_b32_e64 v77, v221, v77, s[8:9]
	v_cmp_gt_i32_e64 s[8:9], v113, v149
	s_nop 1
	v_cndmask_b32_e64 v112, v82, v112, s[8:9]
	v_cmp_lt_i32_e64 s[8:9], v113, v149
	v_add_u32_e32 v113, 0xffffff91, v1
	s_nop 0
	v_cndmask_b32_e64 v82, v112, v82, s[8:9]
	v_cndmask_b32_e64 v83, v221, v83, s[8:9]
	v_cmp_le_i32_e64 s[8:9], v114, v149
	v_mov_b32_e32 v112, s41
	v_add_u32_e32 v114, 0xffffff93, v1
	v_cndmask_b32_e64 v84, v221, v84, s[8:9]
	v_cmp_le_i32_e64 s[8:9], v115, v149
	v_cndmask_b32_e32 v86, v86, v112, vcc
	v_add_u32_e32 v115, 0xffffff94, v1
	v_cndmask_b32_e64 v85, v221, v85, s[8:9]
	v_cmp_gt_i32_e64 s[8:9], v113, v148
	v_add_u32_e32 v113, 0xffffff92, v1
	v_cmp_le_i32_e32 vcc, v113, v149
	v_cndmask_b32_e64 v90, v90, v112, s[8:9]
	v_cmp_le_i32_e64 s[8:9], v113, v148
	v_cndmask_b32_e32 v87, v221, v87, vcc
	v_cmp_le_i32_e32 vcc, v114, v149
	v_add_u32_e32 v113, 0xffffffa1, v1
	v_cndmask_b32_e64 v91, v221, v91, s[8:9]
	v_cndmask_b32_e32 v88, v221, v88, vcc
	v_cmp_le_i32_e32 vcc, v115, v149
	v_cmp_le_i32_e64 s[8:9], v114, v148
	v_add_u32_e32 v114, 0xffffffa2, v1
	v_cndmask_b32_e32 v89, v221, v89, vcc
	v_cmp_gt_i32_e32 vcc, v113, v148
	v_cndmask_b32_e64 v92, v221, v92, s[8:9]
	v_cmp_le_i32_e64 s[8:9], v115, v148
	v_cndmask_b32_e32 v78, v78, v112, vcc
	v_cmp_le_i32_e32 vcc, v114, v148
	v_add_u32_e32 v115, 0xffffffa3, v1
	v_cndmask_b32_e64 v93, v221, v93, s[8:9]
	v_cndmask_b32_e32 v79, v221, v79, vcc
	v_cmp_le_i32_e32 vcc, v115, v148
	s_nop 1
	v_cndmask_b32_e32 v80, v221, v80, vcc
	v_cmp_le_i32_e32 vcc, v116, v148
	s_nop 1
	v_cndmask_b32_e32 v81, v221, v81, vcc
	v_cmp_gt_i32_e32 vcc, v113, v149
	v_add_u32_e32 v113, 0xffffffb1, v1
	s_nop 0
	v_cndmask_b32_e32 v66, v66, v112, vcc
	v_cmp_le_i32_e32 vcc, v114, v149
	v_add_u32_e32 v114, 0xffffffb2, v1
	s_nop 0
	v_cndmask_b32_e32 v67, v221, v67, vcc
	v_cmp_le_i32_e32 vcc, v115, v149
	v_add_u32_e32 v115, 0xffffffb3, v1
	v_add_u32_e32 v1, 0xffffffb4, v1
	v_cndmask_b32_e32 v68, v221, v68, vcc
	v_cmp_le_i32_e32 vcc, v116, v149
	s_nop 1
	v_cndmask_b32_e32 v69, v221, v69, vcc
	v_cmp_gt_i32_e32 vcc, v113, v148
	s_nop 1
	v_cndmask_b32_e32 v94, v94, v112, vcc
	v_cmp_le_i32_e32 vcc, v114, v148
	s_nop 1
	v_cndmask_b32_e32 v95, v221, v95, vcc
	v_cmp_le_i32_e32 vcc, v115, v148
	s_nop 1
	v_cndmask_b32_e32 v96, v221, v96, vcc
	v_cmp_le_i32_e32 vcc, v1, v148
	s_nop 1
	v_cndmask_b32_e32 v97, v221, v97, vcc
	v_cmp_gt_i32_e32 vcc, v113, v149
	s_nop 1
	v_cndmask_b32_e32 v70, v70, v112, vcc
	v_cmp_le_i32_e32 vcc, v114, v149
	s_nop 1
	v_cndmask_b32_e32 v71, v221, v71, vcc
	v_cmp_le_i32_e32 vcc, v115, v149
	s_nop 1
	v_cndmask_b32_e32 v72, v221, v72, vcc
	v_cmp_le_i32_e32 vcc, v1, v149
	s_nop 1
	v_cndmask_b32_e32 v73, v221, v73, vcc
.LBB0_179:
	s_or_b64 exec, exec, s[78:79]
	v_max_f32_e32 v1, v76, v77
	v_max_f32_e32 v112, v92, v93
	v_max3_f32 v1, v74, v75, v1
	v_max3_f32 v112, v90, v91, v112
	v_max3_f32 v1, v1, s41, v112
	v_max_f32_e32 v112, v80, v81
	v_max_f32_e32 v114, v96, v96
	v_max_f32_e32 v113, v114, v97
	v_max3_f32 v112, v78, v79, v112
	v_max3_f32 v113, v94, v95, v113
	v_max3_f32 v1, v1, v112, v113
	ds_bpermute_b32 v112, v135, v1
	s_waitcnt lgkmcnt(0)
	v_max_f32_e32 v1, v1, v112
	ds_bpermute_b32 v112, v101, v1
	s_waitcnt lgkmcnt(0)
	v_max3_f32 v1, v111, v1, v112
	v_sub_f32_e32 v74, v74, v1
	v_sub_f32_e32 v112, v111, v1
	v_exp_f32_e32 v111, v74
	v_sub_f32_e32 v74, v75, v1
	v_exp_f32_e32 v113, v74
	v_sub_f32_e32 v74, v76, v1
	v_exp_f32_e32 v115, v74
	v_sub_f32_e32 v74, v77, v1
	v_exp_f32_e32 v117, v74
	v_sub_f32_e32 v74, v90, v1
	v_exp_f32_e32 v119, v74
	v_sub_f32_e32 v74, v91, v1
	v_exp_f32_e32 v91, v74
	v_sub_f32_e32 v74, v92, v1
	v_exp_f32_e32 v121, v74
	v_sub_f32_e32 v74, v93, v1
	v_exp_f32_e32 v93, v74
	v_sub_f32_e32 v74, v78, v1
	v_exp_f32_e32 v123, v74
	v_sub_f32_e32 v74, v79, v1
	v_exp_f32_e32 v125, v74
	v_sub_f32_e32 v74, v80, v1
	v_exp_f32_e32 v127, v74
	v_sub_f32_e32 v74, v81, v1
	v_exp_f32_e32 v129, v74
	v_sub_f32_e32 v74, v94, v1
	v_max_f32_e32 v90, v84, v85
	v_max_f32_e32 v92, v88, v89
	v_max3_f32 v90, v82, v83, v90
	v_max3_f32 v92, v86, v87, v92
	v_exp_f32_e32 v131, v74
	v_sub_f32_e32 v74, v95, v1
	v_max3_f32 v90, v90, s41, v92
	v_exp_f32_e32 v95, v74
	v_sub_f32_e32 v74, v96, v1
	v_max_f32_e32 v92, v68, v69
	v_max_f32_e32 v94, v72, v73
	v_max3_f32 v92, v66, v67, v92
	v_max3_f32 v94, v70, v71, v94
	v_max3_f32 v90, v90, v92, v94
	ds_bpermute_b32 v92, v135, v90
	v_exp_f32_e32 v134, v112
	v_exp_f32_e32 v133, v74
	v_sub_f32_e32 v74, v97, v1
	v_exp_f32_e32 v97, v74
	s_waitcnt lgkmcnt(0)
	v_max_f32_e32 v90, v90, v92
	ds_bpermute_b32 v92, v101, v90
	v_pk_mul_f32 v[80:81], v[52:53], v[134:135] op_sel_hi:[1,0]
	v_pk_mul_f32 v[78:79], v[50:51], v[134:135] op_sel_hi:[1,0]
	v_pk_mul_f32 v[76:77], v[56:57], v[134:135] op_sel_hi:[1,0]
	v_pk_mul_f32 v[74:75], v[54:55], v[134:135] op_sel_hi:[1,0]
	s_waitcnt lgkmcnt(0)
	v_max3_f32 v151, v110, v90, v92
	v_sub_f32_e32 v82, v82, v151
	v_sub_f32_e32 v152, v110, v151
	v_exp_f32_e32 v110, v82
	v_sub_f32_e32 v82, v83, v151
	v_exp_f32_e32 v112, v82
	v_sub_f32_e32 v82, v84, v151
	v_exp_f32_e32 v114, v82
	v_sub_f32_e32 v82, v85, v151
	v_sub_f32_e32 v66, v66, v151
	v_exp_f32_e32 v116, v82
	v_sub_f32_e32 v82, v86, v151
	v_exp_f32_e32 v122, v66
	v_sub_f32_e32 v66, v67, v151
	v_exp_f32_e32 v118, v82
	v_sub_f32_e32 v82, v87, v151
	v_exp_f32_e32 v124, v66
	v_pk_add_f32 v[66:67], v[110:111], 0 op_sel_hi:[1,0]
	v_exp_f32_e32 v90, v82
	v_sub_f32_e32 v82, v88, v151
	v_pk_add_f32 v[66:67], v[112:113], v[66:67]
	v_exp_f32_e32 v120, v82
	v_sub_f32_e32 v82, v89, v151
	v_pk_add_f32 v[66:67], v[114:115], v[66:67]
	v_exp_f32_e32 v92, v82
	v_pk_add_f32 v[66:67], v[116:117], v[66:67]
	v_sub_f32_e32 v68, v68, v151
	v_pk_add_f32 v[66:67], v[118:119], v[66:67]
	v_exp_f32_e32 v126, v68
	v_pk_add_f32 v[66:67], v[90:91], v[66:67]
	v_sub_f32_e32 v68, v69, v151
	v_pk_add_f32 v[66:67], v[120:121], v[66:67]
	v_exp_f32_e32 v128, v68
	v_pk_add_f32 v[66:67], v[92:93], v[66:67]
	v_sub_f32_e32 v68, v70, v151
	v_pk_add_f32 v[66:67], v[122:123], v[66:67]
	v_exp_f32_e32 v130, v68
	v_sub_f32_e32 v68, v71, v151
	v_pk_add_f32 v[66:67], v[124:125], v[66:67]
	v_exp_f32_e32 v94, v68
	v_sub_f32_e32 v68, v72, v151
	v_exp_f32_e32 v132, v68
	v_sub_f32_e32 v68, v73, v151
	v_pk_add_f32 v[66:67], v[126:127], v[66:67]
	v_exp_f32_e32 v96, v68
	v_pk_add_f32 v[66:67], v[128:129], v[66:67]
	v_exp_f32_e32 v82, v152
	v_pk_add_f32 v[66:67], v[130:131], v[66:67]
	v_mov_b32_e32 v83, v134
	v_pk_add_f32 v[66:67], v[94:95], v[66:67]
	v_pk_add_f32 v[66:67], v[132:133], v[66:67]
	v_pk_mul_f32 v[68:69], v[36:37], v[82:83] op_sel_hi:[1,0]
	v_pk_add_f32 v[66:67], v[96:97], v[66:67]
	v_pk_mul_f32 v[72:73], v[40:41], v[82:83] op_sel_hi:[1,0]
	v_pk_fma_f32 v[104:105], v[104:105], v[82:83], v[66:67]
	v_pk_mul_f32 v[66:67], v[34:35], v[82:83] op_sel_hi:[1,0]
	v_pk_mul_f32 v[70:71], v[38:39], v[82:83] op_sel_hi:[1,0]
	v_pk_mul_f32 v[44:45], v[44:45], v[82:83] op_sel_hi:[1,0]
	v_pk_mul_f32 v[42:43], v[42:43], v[82:83] op_sel_hi:[1,0]
	v_pk_mul_f32 v[36:37], v[48:49], v[82:83] op_sel_hi:[1,0]
	v_pk_mul_f32 v[34:35], v[46:47], v[82:83] op_sel_hi:[1,0]
	ds_read_b128 v[154:157], v188 offset:25088
	ds_read_b128 v[158:161], v188 offset:27136
	ds_read_b128 v[162:165], v188 offset:29184
	ds_read_b128 v[166:169], v188 offset:31232
	ds_read_b128 v[170:173], v189 offset:27136
	ds_read_b128 v[174:177], v189 offset:25088
	ds_read_b128 v[178:181], v189 offset:29184
	ds_read_b128 v[182:185], v189 offset:31232
	v_cvt_pk_bf16_f32 v54, v111, v113
	v_cvt_pk_bf16_f32 v55, v115, v117
	v_cvt_pk_bf16_f32 v56, v119, v91
	v_cvt_pk_bf16_f32 v57, v121, v93
	v_cvt_pk_bf16_f32 v38, v110, v112
	v_cvt_pk_bf16_f32 v39, v114, v116
	v_cvt_pk_bf16_f32 v40, v118, v90
	v_cvt_pk_bf16_f32 v41, v120, v92
	v_pk_mul_f32 v[60:61], v[60:61], v[134:135] op_sel_hi:[1,0]
	s_waitcnt lgkmcnt(7)
	v_mfma_f32_16x16x32_bf16 v[78:81], v[154:157], v[54:57], v[78:81]
	v_mul_f32_e64 v58, v58, v134
	v_mul_f32_e64 v59, v59, v134
	v_pk_mul_f32 v[52:53], v[64:65], v[134:135] op_sel_hi:[1,0]
	v_pk_mul_f32 v[50:51], v[62:63], v[134:135] op_sel_hi:[1,0]
	v_mfma_f32_16x16x32_bf16 v[66:69], v[154:157], v[38:41], v[66:69]
	v_cvt_pk_bf16_f32 v62, v123, v125
	s_waitcnt lgkmcnt(6)
	v_mfma_f32_16x16x32_bf16 v[74:77], v[158:161], v[54:57], v[74:77]
	v_cvt_pk_bf16_f32 v63, v127, v129
	v_cvt_pk_bf16_f32 v64, v131, v95
	v_cvt_pk_bf16_f32 v65, v133, v97
	v_mfma_f32_16x16x32_bf16 v[70:73], v[158:161], v[38:41], v[70:73]
	v_cvt_pk_bf16_f32 v46, v122, v124
	v_cvt_pk_bf16_f32 v47, v126, v128
	s_waitcnt lgkmcnt(5)
	v_mfma_f32_16x16x32_bf16 v[58:61], v[162:165], v[54:57], v[58:61]
	v_cvt_pk_bf16_f32 v48, v130, v94
	v_cvt_pk_bf16_f32 v49, v132, v96
	v_mov_b32_e32 v110, v151
	v_mfma_f32_16x16x32_bf16 v[42:45], v[162:165], v[38:41], v[42:45]
	v_mov_b32_e32 v111, v1
	s_waitcnt lgkmcnt(4)
	v_mfma_f32_16x16x32_bf16 v[86:89], v[166:169], v[54:57], v[50:53]
	v_mfma_f32_16x16x32_bf16 v[82:85], v[166:169], v[38:41], v[34:37]
	s_waitcnt lgkmcnt(2)
	v_mfma_f32_16x16x32_bf16 v[50:53], v[174:177], v[62:65], v[78:81]
	v_mfma_f32_16x16x32_bf16 v[34:37], v[174:177], v[46:49], v[66:69]
	s_waitcnt lgkmcnt(1)
	v_mfma_f32_16x16x32_bf16 v[58:61], v[178:181], v[62:65], v[58:61]
	v_mfma_f32_16x16x32_bf16 v[42:45], v[178:181], v[46:49], v[42:45]
	v_mfma_f32_16x16x32_bf16 v[54:57], v[170:173], v[62:65], v[74:77]
	v_mfma_f32_16x16x32_bf16 v[38:41], v[170:173], v[46:49], v[70:73]
	s_waitcnt lgkmcnt(0)
	v_mfma_f32_16x16x32_bf16 v[62:65], v[182:185], v[62:65], v[86:89]
	v_mfma_f32_16x16x32_bf16 v[46:49], v[182:185], v[46:49], v[82:85]
.LBB0_180:
	s_or_b64 exec, exec, s[16:17]
	s_add_i32 s16, s65, -2
	s_cmp_lt_u32 s16, s30
	s_cselect_b64 s[8:9], -1, 0
	s_cmp_ge_u32 s16, s30
	s_cbranch_scc1 .LBB0_182
	s_waitcnt vmcnt(2)
	ds_write_b128 v138, v[10:13] offset:16896
	ds_write_b64 v139, v[14:15] offset:33280
	ds_write_b64 v140, v[16:17] offset:33280

.LBB0_185:
	s_sub_i32 s8, s81, 63
	v_cmp_le_i32_e32 vcc, s8, v141
	s_and_b64 s[8:9], s[12:13], vcc
	s_and_saveexec_b64 s[16:17], s[8:9]
	s_cbranch_execz .LBB0_189
	ds_read_b128 v[66:69], v142 offset:256
	ds_read_b128 v[70:73], v142 offset:320
	ds_read_b128 v[74:77], v142 offset:384
	ds_read_b128 v[78:81], v142 offset:448
	ds_read_b128 v[154:157], v186 offset:16896
	ds_read_b128 v[158:161], v186 offset:18944
	ds_read_b128 v[162:165], v186 offset:20992
	ds_read_b128 v[166:169], v186 offset:23040
	ds_read_b128 v[170:173], v187 offset:16896
	ds_read_b128 v[174:177], v187 offset:18944
	ds_read_b128 v[178:181], v187 offset:20992
	ds_read_b128 v[182:185], v187 offset:23040
	v_cmp_gt_i32_e32 vcc, s81, v136
	s_waitcnt lgkmcnt(7)
	v_mfma_f32_16x16x32_bf16 v[86:89], v[154:157], v[30:33], v[66:69]
	v_mfma_f32_16x16x32_bf16 v[82:85], v[154:157], v[26:29], v[66:69]
	s_waitcnt lgkmcnt(6)
	v_mfma_f32_16x16x32_bf16 v[90:93], v[158:161], v[30:33], v[70:73]
	v_mfma_f32_16x16x32_bf16 v[70:73], v[158:161], v[26:29], v[70:73]
	s_waitcnt lgkmcnt(5)
	v_mfma_f32_16x16x32_bf16 v[94:97], v[162:165], v[30:33], v[74:77]
	v_mfma_f32_16x16x32_bf16 v[112:115], v[162:165], v[26:29], v[74:77]
	s_waitcnt lgkmcnt(4)
	v_mfma_f32_16x16x32_bf16 v[116:119], v[166:169], v[30:33], v[78:81]
	v_mfma_f32_16x16x32_bf16 v[78:81], v[166:169], v[26:29], v[78:81]
	s_waitcnt lgkmcnt(3)
	v_mfma_f32_16x16x32_bf16 v[66:69], v[170:173], v[22:25], v[86:89]
	v_mfma_f32_16x16x32_bf16 v[86:89], v[170:173], v[18:21], v[82:85]
	s_waitcnt lgkmcnt(2)
	v_mfma_f32_16x16x32_bf16 v[90:93], v[174:177], v[22:25], v[90:93]
	v_mfma_f32_16x16x32_bf16 v[74:77], v[174:177], v[18:21], v[70:73]
	s_waitcnt lgkmcnt(1)
	v_mfma_f32_16x16x32_bf16 v[82:85], v[178:181], v[22:25], v[94:97]
	v_mfma_f32_16x16x32_bf16 v[70:73], v[178:181], v[18:21], v[112:115]
	s_waitcnt lgkmcnt(0)
	v_mfma_f32_16x16x32_bf16 v[94:97], v[182:185], v[22:25], v[116:119]
	v_mfma_f32_16x16x32_bf16 v[78:81], v[182:185], v[18:21], v[78:81]
	s_and_saveexec_b64 s[78:79], vcc
	s_cbranch_execz .LBB0_188
	v_add_u32_e32 v1, s81, v137
	v_subrev_u32_e32 v113, 63, v1
	v_mov_b32_e32 v112, s41
	v_cmp_gt_i32_e32 vcc, v113, v148
	v_cmp_lt_i32_e64 s[8:9], v113, v148
	v_subrev_u32_e32 v114, 61, v1
	v_cndmask_b32_e32 v112, v66, v112, vcc
	v_cndmask_b32_e64 v66, v112, v66, s[8:9]
	v_cndmask_b32_e64 v67, v221, v67, s[8:9]
	v_cmp_le_i32_e64 s[8:9], v114, v148
	v_subrev_u32_e32 v115, 60, v1
	v_mov_b32_e32 v112, s41
	v_cndmask_b32_e64 v68, v221, v68, s[8:9]
	v_cmp_le_i32_e64 s[8:9], v115, v148
	v_subrev_u32_e32 v116, 28, v1
	s_nop 0
	v_cndmask_b32_e64 v69, v221, v69, s[8:9]
	v_cmp_gt_i32_e64 s[8:9], v113, v149
	s_nop 1
	v_cndmask_b32_e64 v112, v86, v112, s[8:9]
	v_cmp_lt_i32_e64 s[8:9], v113, v149
	v_subrev_u32_e32 v113, 47, v1
	s_nop 0
	v_cndmask_b32_e64 v86, v112, v86, s[8:9]
	v_cndmask_b32_e64 v87, v221, v87, s[8:9]
	v_cmp_le_i32_e64 s[8:9], v114, v149
	v_mov_b32_e32 v112, s41
	v_subrev_u32_e32 v114, 45, v1
	v_cndmask_b32_e64 v88, v221, v88, s[8:9]
	v_cmp_le_i32_e64 s[8:9], v115, v149
	v_cndmask_b32_e32 v74, v74, v112, vcc
	v_subrev_u32_e32 v115, 44, v1
	v_cndmask_b32_e64 v89, v221, v89, s[8:9]
	v_cmp_gt_i32_e64 s[8:9], v113, v148
	v_subrev_u32_e32 v113, 46, v1
	v_cmp_le_i32_e32 vcc, v113, v149
	v_cndmask_b32_e64 v90, v90, v112, s[8:9]
	v_cmp_le_i32_e64 s[8:9], v113, v148
	v_cndmask_b32_e32 v75, v221, v75, vcc
	v_cmp_le_i32_e32 vcc, v114, v149
	v_subrev_u32_e32 v113, 31, v1
	v_cndmask_b32_e64 v91, v221, v91, s[8:9]
	v_cndmask_b32_e32 v76, v221, v76, vcc
	v_cmp_le_i32_e32 vcc, v115, v149
	v_cmp_le_i32_e64 s[8:9], v114, v148
	v_subrev_u32_e32 v114, 30, v1
	v_cndmask_b32_e32 v77, v221, v77, vcc
	v_cmp_gt_i32_e32 vcc, v113, v148
	v_cndmask_b32_e64 v92, v221, v92, s[8:9]
	v_cmp_le_i32_e64 s[8:9], v115, v148
	v_cndmask_b32_e32 v82, v82, v112, vcc
	v_cmp_le_i32_e32 vcc, v114, v148
	v_subrev_u32_e32 v115, 29, v1
	v_cndmask_b32_e64 v93, v221, v93, s[8:9]
	v_cndmask_b32_e32 v83, v221, v83, vcc
	v_cmp_le_i32_e32 vcc, v115, v148
	s_nop 1
	v_cndmask_b32_e32 v84, v221, v84, vcc
	v_cmp_le_i32_e32 vcc, v116, v148
	s_nop 1
	v_cndmask_b32_e32 v85, v221, v85, vcc
	v_cmp_gt_i32_e32 vcc, v113, v149
	v_add_u32_e32 v113, -15, v1
	s_nop 0
	v_cndmask_b32_e32 v70, v70, v112, vcc
	v_cmp_le_i32_e32 vcc, v114, v149
	v_add_u32_e32 v114, -14, v1
	s_nop 0
	v_cndmask_b32_e32 v71, v221, v71, vcc
	v_cmp_le_i32_e32 vcc, v115, v149
	v_add_u32_e32 v115, -13, v1
	v_add_u32_e32 v1, -12, v1
	v_cndmask_b32_e32 v72, v221, v72, vcc
	v_cmp_le_i32_e32 vcc, v116, v149
	s_nop 1
	v_cndmask_b32_e32 v73, v221, v73, vcc
	v_cmp_gt_i32_e32 vcc, v113, v148
	s_nop 1
	v_cndmask_b32_e32 v94, v94, v112, vcc
	v_cmp_le_i32_e32 vcc, v114, v148
	s_nop 1
	v_cndmask_b32_e32 v95, v221, v95, vcc
	v_cmp_le_i32_e32 vcc, v115, v148
	s_nop 1
	v_cndmask_b32_e32 v96, v221, v96, vcc
	v_cmp_le_i32_e32 vcc, v1, v148
	s_nop 1
	v_cndmask_b32_e32 v97, v221, v97, vcc
	v_cmp_gt_i32_e32 vcc, v113, v149
	s_nop 1
	v_cndmask_b32_e32 v78, v78, v112, vcc
	v_cmp_le_i32_e32 vcc, v114, v149
	s_nop 1
	v_cndmask_b32_e32 v79, v221, v79, vcc
	v_cmp_le_i32_e32 vcc, v115, v149
	s_nop 1
	v_cndmask_b32_e32 v80, v221, v80, vcc
	v_cmp_le_i32_e32 vcc, v1, v149
	s_nop 1
	v_cndmask_b32_e32 v81, v221, v81, vcc
.LBB0_188:
	s_or_b64 exec, exec, s[78:79]
	v_max_f32_e32 v1, v68, v69
	v_max_f32_e32 v112, v92, v93
	v_max3_f32 v1, v66, v67, v1
	v_max3_f32 v112, v90, v91, v112
	v_max3_f32 v1, v1, s41, v112
	v_max_f32_e32 v112, v84, v85
	v_max_f32_e32 v114, v96, v96
	v_max_f32_e32 v113, v114, v97
	v_max3_f32 v112, v82, v83, v112
	v_max3_f32 v113, v94, v95, v113
	v_max3_f32 v1, v1, v112, v113
	ds_bpermute_b32 v112, v135, v1
	s_waitcnt lgkmcnt(0)
	v_max_f32_e32 v1, v1, v112
	ds_bpermute_b32 v112, v101, v1
	s_waitcnt lgkmcnt(0)
	v_max3_f32 v1, v111, v1, v112
	v_sub_f32_e32 v66, v66, v1
	v_sub_f32_e32 v112, v111, v1
	v_exp_f32_e32 v111, v66
	v_sub_f32_e32 v66, v67, v1
	v_exp_f32_e32 v113, v66
	v_sub_f32_e32 v66, v68, v1
	v_exp_f32_e32 v115, v66
	v_sub_f32_e32 v66, v69, v1
	v_exp_f32_e32 v117, v66
	v_sub_f32_e32 v66, v90, v1
	v_exp_f32_e32 v119, v66
	v_sub_f32_e32 v66, v91, v1
	v_exp_f32_e32 v91, v66
	v_sub_f32_e32 v66, v92, v1
	v_exp_f32_e32 v121, v66
	v_sub_f32_e32 v66, v93, v1
	v_exp_f32_e32 v93, v66
	v_sub_f32_e32 v66, v82, v1
	v_exp_f32_e32 v123, v66
	v_sub_f32_e32 v66, v83, v1
	v_exp_f32_e32 v125, v66
	v_sub_f32_e32 v66, v84, v1
	v_exp_f32_e32 v127, v66
	v_sub_f32_e32 v66, v85, v1
	v_exp_f32_e32 v129, v66
	v_sub_f32_e32 v66, v94, v1
	v_max_f32_e32 v90, v88, v89
	v_max_f32_e32 v92, v76, v77
	v_max3_f32 v90, v86, v87, v90
	v_max3_f32 v92, v74, v75, v92
	v_exp_f32_e32 v131, v66
	v_sub_f32_e32 v66, v95, v1
	v_max3_f32 v90, v90, s41, v92
	v_exp_f32_e32 v95, v66
	v_sub_f32_e32 v66, v96, v1
	v_max_f32_e32 v92, v72, v73
	v_max_f32_e32 v94, v80, v81
	v_max3_f32 v92, v70, v71, v92
	v_max3_f32 v94, v78, v79, v94
	v_max3_f32 v90, v90, v92, v94
	ds_bpermute_b32 v92, v135, v90
	v_exp_f32_e32 v152, v112
	v_exp_f32_e32 v133, v66
	v_sub_f32_e32 v66, v97, v1
	v_exp_f32_e32 v97, v66
	s_waitcnt lgkmcnt(0)
	v_max_f32_e32 v90, v90, v92
	ds_bpermute_b32 v92, v101, v90
	v_pk_mul_f32 v[84:85], v[52:53], v[152:153] op_sel_hi:[1,0]
	v_pk_mul_f32 v[82:83], v[50:51], v[152:153] op_sel_hi:[1,0]
	v_pk_mul_f32 v[68:69], v[56:57], v[152:153] op_sel_hi:[1,0]
	v_pk_mul_f32 v[66:67], v[54:55], v[152:153] op_sel_hi:[1,0]
	s_waitcnt lgkmcnt(0)
	v_max3_f32 v134, v110, v90, v92
	v_sub_f32_e32 v86, v86, v134
	v_sub_f32_e32 v151, v110, v134
	v_exp_f32_e32 v110, v86
	v_sub_f32_e32 v86, v87, v134
	v_exp_f32_e32 v112, v86
	v_sub_f32_e32 v86, v88, v134
	v_sub_f32_e32 v74, v74, v134
	v_exp_f32_e32 v114, v86
	v_sub_f32_e32 v86, v89, v134
	v_exp_f32_e32 v118, v74
	v_sub_f32_e32 v74, v75, v134
	v_exp_f32_e32 v116, v86
	v_exp_f32_e32 v90, v74
	v_sub_f32_e32 v74, v76, v134
	v_sub_f32_e32 v70, v70, v134
	v_exp_f32_e32 v120, v74
	v_pk_add_f32 v[74:75], v[110:111], 0 op_sel_hi:[1,0]
	v_exp_f32_e32 v122, v70
	v_sub_f32_e32 v70, v71, v134
	v_pk_add_f32 v[74:75], v[112:113], v[74:75]
	v_exp_f32_e32 v124, v70
	v_sub_f32_e32 v70, v72, v134
	v_pk_add_f32 v[74:75], v[114:115], v[74:75]
	v_sub_f32_e32 v76, v77, v134
	v_exp_f32_e32 v126, v70
	v_sub_f32_e32 v70, v73, v134
	v_pk_add_f32 v[74:75], v[116:117], v[74:75]
	v_exp_f32_e32 v92, v76
	v_exp_f32_e32 v128, v70
	v_sub_f32_e32 v70, v78, v134
	v_pk_add_f32 v[74:75], v[118:119], v[74:75]
	v_exp_f32_e32 v130, v70
	v_sub_f32_e32 v70, v79, v134
	v_pk_add_f32 v[74:75], v[90:91], v[74:75]
	v_exp_f32_e32 v94, v70
	v_sub_f32_e32 v70, v80, v134
	v_pk_add_f32 v[74:75], v[120:121], v[74:75]
	v_exp_f32_e32 v132, v70
	v_sub_f32_e32 v70, v81, v134
	v_exp_f32_e32 v96, v70
	v_pk_add_f32 v[70:71], v[92:93], v[74:75]
	v_exp_f32_e32 v78, v151
	v_pk_add_f32 v[70:71], v[122:123], v[70:71]
	v_mov_b32_e32 v79, v152
	v_pk_add_f32 v[70:71], v[124:125], v[70:71]
	v_pk_add_f32 v[70:71], v[126:127], v[70:71]
	v_pk_mul_f32 v[76:77], v[36:37], v[78:79] op_sel_hi:[1,0]
	v_pk_add_f32 v[70:71], v[128:129], v[70:71]
	v_pk_mul_f32 v[74:75], v[34:35], v[78:79] op_sel_hi:[1,0]
	v_pk_add_f32 v[70:71], v[130:131], v[70:71]
	v_pk_mul_f32 v[72:73], v[40:41], v[78:79] op_sel_hi:[1,0]
	v_pk_add_f32 v[70:71], v[94:95], v[70:71]
	v_pk_mul_f32 v[44:45], v[44:45], v[78:79] op_sel_hi:[1,0]
	v_pk_add_f32 v[70:71], v[132:133], v[70:71]
	v_pk_mul_f32 v[42:43], v[42:43], v[78:79] op_sel_hi:[1,0]
	v_pk_add_f32 v[70:71], v[96:97], v[70:71]
	v_pk_mul_f32 v[36:37], v[48:49], v[78:79] op_sel_hi:[1,0]
	v_pk_fma_f32 v[104:105], v[104:105], v[78:79], v[70:71]
	v_pk_mul_f32 v[70:71], v[38:39], v[78:79] op_sel_hi:[1,0]
	v_pk_mul_f32 v[34:35], v[46:47], v[78:79] op_sel_hi:[1,0]
	ds_read_b128 v[154:157], v188 offset:33280
	ds_read_b128 v[158:161], v188 offset:35328
	ds_read_b128 v[162:165], v188 offset:37376
	ds_read_b128 v[166:169], v188 offset:39424
	ds_read_b128 v[170:173], v189 offset:35328
	ds_read_b128 v[174:177], v189 offset:33280
	ds_read_b128 v[178:181], v189 offset:37376
	ds_read_b128 v[182:185], v189 offset:39424
	v_cvt_pk_bf16_f32 v54, v111, v113
	v_cvt_pk_bf16_f32 v55, v115, v117
	v_cvt_pk_bf16_f32 v56, v119, v91
	v_cvt_pk_bf16_f32 v57, v121, v93
	v_cvt_pk_bf16_f32 v38, v110, v112
	v_cvt_pk_bf16_f32 v39, v114, v116
	v_cvt_pk_bf16_f32 v40, v118, v90
	v_cvt_pk_bf16_f32 v41, v120, v92
	v_pk_mul_f32 v[60:61], v[60:61], v[152:153] op_sel_hi:[1,0]
	s_waitcnt lgkmcnt(7)
	v_mfma_f32_16x16x32_bf16 v[82:85], v[154:157], v[54:57], v[82:85]
	v_mul_f32_e64 v58, v58, v152
	v_mul_f32_e64 v59, v59, v152
	v_pk_mul_f32 v[52:53], v[64:65], v[152:153] op_sel_hi:[1,0]
	v_pk_mul_f32 v[50:51], v[62:63], v[152:153] op_sel_hi:[1,0]
	v_mfma_f32_16x16x32_bf16 v[74:77], v[154:157], v[38:41], v[74:77]
	v_cvt_pk_bf16_f32 v62, v123, v125
	s_waitcnt lgkmcnt(6)
	v_mfma_f32_16x16x32_bf16 v[66:69], v[158:161], v[54:57], v[66:69]
	v_cvt_pk_bf16_f32 v63, v127, v129
	v_cvt_pk_bf16_f32 v64, v131, v95
	v_cvt_pk_bf16_f32 v65, v133, v97
	v_mfma_f32_16x16x32_bf16 v[70:73], v[158:161], v[38:41], v[70:73]
	v_cvt_pk_bf16_f32 v46, v122, v124
	v_cvt_pk_bf16_f32 v47, v126, v128
	s_waitcnt lgkmcnt(5)
	v_mfma_f32_16x16x32_bf16 v[58:61], v[162:165], v[54:57], v[58:61]
	v_cvt_pk_bf16_f32 v48, v130, v94
	v_cvt_pk_bf16_f32 v49, v132, v96
	v_mov_b32_e32 v110, v134
	v_mfma_f32_16x16x32_bf16 v[42:45], v[162:165], v[38:41], v[42:45]
	v_mov_b32_e32 v111, v1
	s_waitcnt lgkmcnt(4)
	v_mfma_f32_16x16x32_bf16 v[86:89], v[166:169], v[54:57], v[50:53]
	v_mfma_f32_16x16x32_bf16 v[78:81], v[166:169], v[38:41], v[34:37]
	s_waitcnt lgkmcnt(3)
	v_mfma_f32_16x16x32_bf16 v[54:57], v[170:173], v[62:65], v[66:69]
	s_waitcnt lgkmcnt(1)
	v_mfma_f32_16x16x32_bf16 v[58:61], v[178:181], v[62:65], v[58:61]
	v_mfma_f32_16x16x32_bf16 v[42:45], v[178:181], v[46:49], v[42:45]
	v_mfma_f32_16x16x32_bf16 v[50:53], v[174:177], v[62:65], v[82:85]
	v_mfma_f32_16x16x32_bf16 v[34:37], v[174:177], v[46:49], v[74:77]
	v_mfma_f32_16x16x32_bf16 v[38:41], v[170:173], v[46:49], v[70:73]
	s_waitcnt lgkmcnt(0)
	v_mfma_f32_16x16x32_bf16 v[62:65], v[182:185], v[62:65], v[86:89]
	v_mfma_f32_16x16x32_bf16 v[46:49], v[182:185], v[46:49], v[78:81]
.LBB0_189:
	s_or_b64 exec, exec, s[16:17]
	s_add_i32 s8, s65, -3
	s_cmp_ge_u32 s8, s80
	s_cbranch_scc1 .LBB0_172
	s_waitcnt vmcnt(2)
	ds_write_b128 v138, v[2:5] offset:8704
	ds_write_b64 v139, v[6:7] offset:25088
	ds_write_b64 v140, v[8:9] offset:25088
	s_branch .LBB0_172

.LBB0_203:
	s_or_b64 exec, exec, s[8:9]
	v_lshlrev_b32_e32 v45, 7, v36
	v_and_b32_e32 v46, 7, v36
	v_bitop3_b32 v36, v36, v1, 7 bitop3:0x6c
	v_lshl_or_b32 v36, v36, 4, v45
	v_add_u32_e32 v138, 0, v36
	v_xor_b32_e32 v36, v43, v1
	v_bitop3_b32 v1, v43, v1, 4 bitop3:0x36
	v_lshlrev_b32_e32 v144, 4, v36
	v_lshlrev_b32_e32 v146, 4, v1
	v_xor_b32_e32 v1, 16, v214
	v_add_u32_e32 v36, 64, v37
	v_cmp_lt_i32_e64 s[8:9], v1, v36
	v_and_b32_e32 v47, 4, v42
	v_lshlrev_b32_e32 v42, 1, v42
	v_cndmask_b32_e64 v1, v214, v1, s[8:9]
	v_lshlrev_b32_e32 v135, 2, v1
	v_xor_b32_e32 v1, 32, v214
	v_cmp_lt_i32_e64 s[8:9], v1, v36
	v_and_b32_e32 v42, 2, v42
	v_or_b32_e32 v48, v42, v47
	v_cndmask_b32_e64 v1, v214, v1, s[8:9]
	s_add_u32 s8, s20, s17
	s_addc_u32 s9, s21, s16
	v_lshl_add_u64 v[106:107], s[8:9], 0, v[40:41]
	s_and_b32 s8, s52, 15
	s_lshl_b32 s8, s8, 7
	s_add_u32 s8, s20, s8
	v_bitop3_b32 v42, v42, v46, v47 bitop3:0x36
	v_bitop3_b32 v46, v48, v46, 1 bitop3:0x36
	s_addc_u32 s9, s21, 0
	v_and_b32_e32 v38, 8, v38
	v_lshlrev_b32_e32 v42, 4, v42
	v_lshlrev_b32_e32 v46, 4, v46
	s_add_u32 s8, s8, s12
	v_add_u32_e32 v136, 0x400, v44
	v_or3_b32 v42, v42, v45, v38
	v_or3_b32 v38, v46, v45, v38
	s_addc_u32 s9, s9, s13
	v_mov_b32_e32 v46, v0
	v_mov_b32_e32 v47, v0
	v_mov_b32_e32 v48, v0
	v_mov_b32_e32 v49, v0
	v_add_u32_e32 v139, 0, v42
	v_add_u32_e32 v140, 0, v38
	v_add_u32_e32 v141, 0x41f, v44
	v_lshlrev_b32_e32 v137, 2, v43
	v_lshl_add_u32 v142, v43, 4, 0
	v_lshlrev_b32_e32 v143, 7, v39
	v_or_b32_e32 v148, v136, v39
	v_lshlrev_b32_e32 v101, 2, v1
	v_add_u32_e32 v151, 0x3c1, v44
	v_lshl_add_u64 v[108:109], s[8:9], 0, v[34:35]
	v_mov_b32_e32 v1, v0
	v_mov_b64_e32 v[64:65], v[48:49]
	v_mov_b64_e32 v[42:43], v[46:47]
	v_mov_b64_e32 v[60:61], v[48:49]
	v_mov_b64_e32 v[38:39], v[46:47]
	v_mov_b64_e32 v[56:57], v[48:49]
	v_mov_b64_e32 v[34:35], v[46:47]
	v_mov_b64_e32 v[52:53], v[48:49]
	v_add_u32_e32 v145, 0, v144
	v_add_u32_e32 v147, 0, v146
	v_or_b32_e32 v149, 16, v148
	v_add_u32_e32 v150, 0, v143
	v_mov_b32_e32 v99, v0
	v_mov_b32_e32 v110, 0xff800000
	s_mov_b32 s30, 0
	s_movk_i32 s65, 0x7f
	s_xor_b64 s[12:13], vcc, -1
	v_mov_b64_e32 v[62:63], v[46:47]
	v_mov_b64_e32 v[44:45], v[48:49]
	v_mov_b64_e32 v[58:59], v[46:47]
	v_mov_b64_e32 v[40:41], v[48:49]
	v_mov_b64_e32 v[54:55], v[46:47]
	v_mov_b64_e32 v[36:37], v[48:49]
	v_mov_b64_e32 v[50:51], v[46:47]
	v_mov_b32_e32 v111, 0xff800000
	v_mov_b64_e32 v[104:105], v[0:1]
	ds_write_b128 v138, v[2:5] offset:8704
	ds_write_b64 v139, v[6:7] offset:25088
	ds_write_b64 v140, v[8:9] offset:25088
	s_waitcnt lgkmcnt(0)
	v_add_u32_e32 v186, v145, v143
	v_add_u32_e32 v187, v147, v143
	v_add_u32_e32 v188, v150, v144
	v_add_u32_e32 v189, v150, v146
	s_waitcnt vmcnt(0)
	s_barrier
	s_branch .LBB0_206

.LBB0_208:
	s_add_i32 s8, s65, 0xffffff81
	v_cmp_le_i32_e32 vcc, s8, v141
	s_and_b64 s[82:83], s[12:13], vcc
	s_and_saveexec_b64 s[80:81], s[82:83]
	s_cbranch_execz .LBB0_212
	ds_read_b128 v[66:69], v142
	ds_read_b128 v[70:73], v142 offset:64
	ds_read_b128 v[74:77], v142 offset:128
	ds_read_b128 v[78:81], v142 offset:192
	ds_read_b128 v[154:157], v186 offset:8704
	ds_read_b128 v[158:161], v186 offset:10752
	ds_read_b128 v[162:165], v186 offset:12800
	ds_read_b128 v[166:169], v186 offset:14848
	ds_read_b128 v[170:173], v187 offset:8704
	ds_read_b128 v[174:177], v187 offset:10752
	ds_read_b128 v[178:181], v187 offset:12800
	ds_read_b128 v[182:185], v187 offset:14848
	v_cmp_gt_i32_e32 vcc, s8, v151
	s_waitcnt lgkmcnt(7)
	v_mfma_f32_16x16x32_bf16 v[86:89], v[154:157], v[30:33], v[66:69]
	v_mfma_f32_16x16x32_bf16 v[66:69], v[154:157], v[26:29], v[66:69]
	s_waitcnt lgkmcnt(6)
	v_mfma_f32_16x16x32_bf16 v[90:93], v[158:161], v[30:33], v[70:73]
	v_mfma_f32_16x16x32_bf16 v[70:73], v[158:161], v[26:29], v[70:73]
	s_waitcnt lgkmcnt(5)
	v_mfma_f32_16x16x32_bf16 v[94:97], v[162:165], v[30:33], v[74:77]
	v_mfma_f32_16x16x32_bf16 v[112:115], v[162:165], v[26:29], v[74:77]
	s_waitcnt lgkmcnt(4)
	v_mfma_f32_16x16x32_bf16 v[116:119], v[166:169], v[30:33], v[78:81]
	v_mfma_f32_16x16x32_bf16 v[120:123], v[166:169], v[26:29], v[78:81]
	s_waitcnt lgkmcnt(3)
	v_mfma_f32_16x16x32_bf16 v[82:85], v[170:173], v[18:21], v[66:69]
	v_mfma_f32_16x16x32_bf16 v[74:77], v[170:173], v[22:25], v[86:89]
	s_waitcnt lgkmcnt(2)
	v_mfma_f32_16x16x32_bf16 v[90:93], v[174:177], v[22:25], v[90:93]
	v_mfma_f32_16x16x32_bf16 v[86:89], v[174:177], v[18:21], v[70:73]
	s_waitcnt lgkmcnt(1)
	v_mfma_f32_16x16x32_bf16 v[78:81], v[178:181], v[22:25], v[94:97]
	v_mfma_f32_16x16x32_bf16 v[66:69], v[178:181], v[18:21], v[112:115]
	s_waitcnt lgkmcnt(0)
	v_mfma_f32_16x16x32_bf16 v[94:97], v[182:185], v[22:25], v[116:119]
	v_mfma_f32_16x16x32_bf16 v[70:73], v[182:185], v[18:21], v[120:123]
	s_and_saveexec_b64 s[82:83], vcc
	s_cbranch_execz .LBB0_211
	v_add_u32_e32 v1, s65, v137
	v_add_u32_e32 v113, 0xffffff81, v1
	v_mov_b32_e32 v112, s41
	v_cmp_gt_i32_e32 vcc, v113, v148
	v_cmp_lt_i32_e64 s[8:9], v113, v148
	v_add_u32_e32 v114, 0xffffff83, v1
	v_cndmask_b32_e32 v112, v74, v112, vcc
	v_cndmask_b32_e64 v74, v112, v74, s[8:9]
	v_cndmask_b32_e64 v75, v221, v75, s[8:9]
	v_cmp_le_i32_e64 s[8:9], v114, v148
	v_add_u32_e32 v115, 0xffffff84, v1
	v_mov_b32_e32 v112, s41
	v_cndmask_b32_e64 v76, v221, v76, s[8:9]
	v_cmp_le_i32_e64 s[8:9], v115, v148
	v_add_u32_e32 v116, 0xffffffa4, v1
	s_nop 0
	v_cndmask_b32_e64 v77, v221, v77, s[8:9]
	v_cmp_gt_i32_e64 s[8:9], v113, v149
	s_nop 1
	v_cndmask_b32_e64 v112, v82, v112, s[8:9]
	v_cmp_lt_i32_e64 s[8:9], v113, v149
	v_add_u32_e32 v113, 0xffffff91, v1
	s_nop 0
	v_cndmask_b32_e64 v82, v112, v82, s[8:9]
	v_cndmask_b32_e64 v83, v221, v83, s[8:9]
	v_cmp_le_i32_e64 s[8:9], v114, v149
	v_mov_b32_e32 v112, s41
	v_add_u32_e32 v114, 0xffffff93, v1
	v_cndmask_b32_e64 v84, v221, v84, s[8:9]
	v_cmp_le_i32_e64 s[8:9], v115, v149
	v_cndmask_b32_e32 v86, v86, v112, vcc
	v_add_u32_e32 v115, 0xffffff94, v1
	v_cndmask_b32_e64 v85, v221, v85, s[8:9]
	v_cmp_gt_i32_e64 s[8:9], v113, v148
	v_add_u32_e32 v113, 0xffffff92, v1
	v_cmp_le_i32_e32 vcc, v113, v149
	v_cndmask_b32_e64 v90, v90, v112, s[8:9]
	v_cmp_le_i32_e64 s[8:9], v113, v148
	v_cndmask_b32_e32 v87, v221, v87, vcc
	v_cmp_le_i32_e32 vcc, v114, v149
	v_add_u32_e32 v113, 0xffffffa1, v1
	v_cndmask_b32_e64 v91, v221, v91, s[8:9]
	v_cndmask_b32_e32 v88, v221, v88, vcc
	v_cmp_le_i32_e32 vcc, v115, v149
	v_cmp_le_i32_e64 s[8:9], v114, v148
	v_add_u32_e32 v114, 0xffffffa2, v1
	v_cndmask_b32_e32 v89, v221, v89, vcc
	v_cmp_gt_i32_e32 vcc, v113, v148
	v_cndmask_b32_e64 v92, v221, v92, s[8:9]
	v_cmp_le_i32_e64 s[8:9], v115, v148
	v_cndmask_b32_e32 v78, v78, v112, vcc
	v_cmp_le_i32_e32 vcc, v114, v148
	v_add_u32_e32 v115, 0xffffffa3, v1
	v_cndmask_b32_e64 v93, v221, v93, s[8:9]
	v_cndmask_b32_e32 v79, v221, v79, vcc
	v_cmp_le_i32_e32 vcc, v115, v148
	s_nop 1
	v_cndmask_b32_e32 v80, v221, v80, vcc
	v_cmp_le_i32_e32 vcc, v116, v148
	s_nop 1
	v_cndmask_b32_e32 v81, v221, v81, vcc
	v_cmp_gt_i32_e32 vcc, v113, v149
	v_add_u32_e32 v113, 0xffffffb1, v1
	s_nop 0
	v_cndmask_b32_e32 v66, v66, v112, vcc
	v_cmp_le_i32_e32 vcc, v114, v149
	v_add_u32_e32 v114, 0xffffffb2, v1
	s_nop 0
	v_cndmask_b32_e32 v67, v221, v67, vcc
	v_cmp_le_i32_e32 vcc, v115, v149
	v_add_u32_e32 v115, 0xffffffb3, v1
	v_add_u32_e32 v1, 0xffffffb4, v1
	v_cndmask_b32_e32 v68, v221, v68, vcc
	v_cmp_le_i32_e32 vcc, v116, v149
	s_nop 1
	v_cndmask_b32_e32 v69, v221, v69, vcc
	v_cmp_gt_i32_e32 vcc, v113, v148
	s_nop 1
	v_cndmask_b32_e32 v94, v94, v112, vcc
	v_cmp_le_i32_e32 vcc, v114, v148
	s_nop 1
	v_cndmask_b32_e32 v95, v221, v95, vcc
	v_cmp_le_i32_e32 vcc, v115, v148
	s_nop 1
	v_cndmask_b32_e32 v96, v221, v96, vcc
	v_cmp_le_i32_e32 vcc, v1, v148
	s_nop 1
	v_cndmask_b32_e32 v97, v221, v97, vcc
	v_cmp_gt_i32_e32 vcc, v113, v149
	s_nop 1
	v_cndmask_b32_e32 v70, v70, v112, vcc
	v_cmp_le_i32_e32 vcc, v114, v149
	s_nop 1
	v_cndmask_b32_e32 v71, v221, v71, vcc
	v_cmp_le_i32_e32 vcc, v115, v149
	s_nop 1
	v_cndmask_b32_e32 v72, v221, v72, vcc
	v_cmp_le_i32_e32 vcc, v1, v149
	s_nop 1
	v_cndmask_b32_e32 v73, v221, v73, vcc
.LBB0_211:
	s_or_b64 exec, exec, s[82:83]
	v_max_f32_e32 v1, v76, v77
	v_max_f32_e32 v112, v92, v93
	v_max3_f32 v1, v74, v75, v1
	v_max3_f32 v112, v90, v91, v112
	v_max3_f32 v1, v1, s41, v112
	v_max_f32_e32 v112, v80, v81
	v_max_f32_e32 v114, v96, v96
	v_max_f32_e32 v113, v114, v97
	v_max3_f32 v112, v78, v79, v112
	v_max3_f32 v113, v94, v95, v113
	v_max3_f32 v1, v1, v112, v113
	ds_bpermute_b32 v112, v135, v1
	s_waitcnt lgkmcnt(0)
	v_max_f32_e32 v1, v1, v112
	ds_bpermute_b32 v112, v101, v1
	s_waitcnt lgkmcnt(0)
	v_max3_f32 v1, v111, v1, v112
	v_sub_f32_e32 v74, v74, v1
	v_sub_f32_e32 v112, v111, v1
	v_exp_f32_e32 v111, v74
	v_sub_f32_e32 v74, v75, v1
	v_exp_f32_e32 v113, v74
	v_sub_f32_e32 v74, v76, v1
	v_exp_f32_e32 v115, v74
	v_sub_f32_e32 v74, v77, v1
	v_exp_f32_e32 v117, v74
	v_sub_f32_e32 v74, v90, v1
	v_exp_f32_e32 v119, v74
	v_sub_f32_e32 v74, v91, v1
	v_exp_f32_e32 v91, v74
	v_sub_f32_e32 v74, v92, v1
	v_exp_f32_e32 v121, v74
	v_sub_f32_e32 v74, v93, v1
	v_exp_f32_e32 v93, v74
	v_sub_f32_e32 v74, v78, v1
	v_exp_f32_e32 v123, v74
	v_sub_f32_e32 v74, v79, v1
	v_exp_f32_e32 v125, v74
	v_sub_f32_e32 v74, v80, v1
	v_exp_f32_e32 v127, v74
	v_sub_f32_e32 v74, v81, v1
	v_exp_f32_e32 v129, v74
	v_sub_f32_e32 v74, v94, v1
	v_max_f32_e32 v90, v84, v85
	v_max_f32_e32 v92, v88, v89
	v_max3_f32 v90, v82, v83, v90
	v_max3_f32 v92, v86, v87, v92
	v_exp_f32_e32 v131, v74
	v_sub_f32_e32 v74, v95, v1
	v_max3_f32 v90, v90, s41, v92
	v_exp_f32_e32 v95, v74
	v_sub_f32_e32 v74, v96, v1
	v_max_f32_e32 v92, v68, v69
	v_max_f32_e32 v94, v72, v73
	v_max3_f32 v92, v66, v67, v92
	v_max3_f32 v94, v70, v71, v94
	v_max3_f32 v90, v90, v92, v94
	ds_bpermute_b32 v92, v135, v90
	v_exp_f32_e32 v134, v112
	v_exp_f32_e32 v133, v74
	v_sub_f32_e32 v74, v97, v1
	v_exp_f32_e32 v97, v74
	s_waitcnt lgkmcnt(0)
	v_max_f32_e32 v90, v90, v92
	ds_bpermute_b32 v92, v101, v90
	v_pk_mul_f32 v[80:81], v[52:53], v[134:135] op_sel_hi:[1,0]
	v_pk_mul_f32 v[78:79], v[50:51], v[134:135] op_sel_hi:[1,0]
	v_pk_mul_f32 v[76:77], v[56:57], v[134:135] op_sel_hi:[1,0]
	v_pk_mul_f32 v[74:75], v[54:55], v[134:135] op_sel_hi:[1,0]
	s_waitcnt lgkmcnt(0)
	v_max3_f32 v152, v110, v90, v92
	v_sub_f32_e32 v82, v82, v152
	v_sub_f32_e32 v153, v110, v152
	v_exp_f32_e32 v110, v82
	v_sub_f32_e32 v82, v83, v152
	v_exp_f32_e32 v112, v82
	v_sub_f32_e32 v82, v84, v152
	v_exp_f32_e32 v114, v82
	v_sub_f32_e32 v82, v85, v152
	v_sub_f32_e32 v66, v66, v152
	v_exp_f32_e32 v116, v82
	v_sub_f32_e32 v82, v86, v152
	v_exp_f32_e32 v122, v66
	v_sub_f32_e32 v66, v67, v152
	v_exp_f32_e32 v118, v82
	v_sub_f32_e32 v82, v87, v152
	v_exp_f32_e32 v124, v66
	v_pk_add_f32 v[66:67], v[110:111], 0 op_sel_hi:[1,0]
	v_exp_f32_e32 v90, v82
	v_sub_f32_e32 v82, v88, v152
	v_pk_add_f32 v[66:67], v[112:113], v[66:67]
	v_exp_f32_e32 v120, v82
	v_sub_f32_e32 v82, v89, v152
	v_pk_add_f32 v[66:67], v[114:115], v[66:67]
	v_exp_f32_e32 v92, v82
	v_pk_add_f32 v[66:67], v[116:117], v[66:67]
	v_sub_f32_e32 v68, v68, v152
	v_pk_add_f32 v[66:67], v[118:119], v[66:67]
	v_exp_f32_e32 v126, v68
	v_pk_add_f32 v[66:67], v[90:91], v[66:67]
	v_sub_f32_e32 v68, v69, v152
	v_pk_add_f32 v[66:67], v[120:121], v[66:67]
	v_exp_f32_e32 v128, v68
	v_pk_add_f32 v[66:67], v[92:93], v[66:67]
	v_sub_f32_e32 v68, v70, v152
	v_pk_add_f32 v[66:67], v[122:123], v[66:67]
	v_exp_f32_e32 v130, v68
	v_sub_f32_e32 v68, v71, v152
	v_pk_add_f32 v[66:67], v[124:125], v[66:67]
	v_exp_f32_e32 v94, v68
	v_sub_f32_e32 v68, v72, v152
	v_exp_f32_e32 v132, v68
	v_sub_f32_e32 v68, v73, v152
	v_pk_add_f32 v[66:67], v[126:127], v[66:67]
	v_exp_f32_e32 v96, v68
	v_pk_add_f32 v[66:67], v[128:129], v[66:67]
	v_exp_f32_e32 v82, v153
	v_pk_add_f32 v[66:67], v[130:131], v[66:67]
	v_mov_b32_e32 v83, v134
	v_pk_add_f32 v[66:67], v[94:95], v[66:67]
	v_pk_add_f32 v[66:67], v[132:133], v[66:67]
	v_pk_mul_f32 v[68:69], v[36:37], v[82:83] op_sel_hi:[1,0]
	v_pk_add_f32 v[66:67], v[96:97], v[66:67]
	v_pk_mul_f32 v[72:73], v[40:41], v[82:83] op_sel_hi:[1,0]
	v_pk_fma_f32 v[104:105], v[104:105], v[82:83], v[66:67]
	v_pk_mul_f32 v[66:67], v[34:35], v[82:83] op_sel_hi:[1,0]
	v_pk_mul_f32 v[70:71], v[38:39], v[82:83] op_sel_hi:[1,0]
	v_pk_mul_f32 v[44:45], v[44:45], v[82:83] op_sel_hi:[1,0]
	v_pk_mul_f32 v[42:43], v[42:43], v[82:83] op_sel_hi:[1,0]
	v_pk_mul_f32 v[36:37], v[48:49], v[82:83] op_sel_hi:[1,0]
	v_pk_mul_f32 v[34:35], v[46:47], v[82:83] op_sel_hi:[1,0]
	ds_read_b128 v[154:157], v188 offset:25088
	ds_read_b128 v[158:161], v188 offset:27136
	ds_read_b128 v[162:165], v188 offset:29184
	ds_read_b128 v[166:169], v188 offset:31232
	ds_read_b128 v[170:173], v189 offset:27136
	ds_read_b128 v[174:177], v189 offset:25088
	ds_read_b128 v[178:181], v189 offset:29184
	ds_read_b128 v[182:185], v189 offset:31232
	v_cvt_pk_bf16_f32 v54, v111, v113
	v_cvt_pk_bf16_f32 v55, v115, v117
	v_cvt_pk_bf16_f32 v56, v119, v91
	v_cvt_pk_bf16_f32 v57, v121, v93
	v_cvt_pk_bf16_f32 v38, v110, v112
	v_cvt_pk_bf16_f32 v39, v114, v116
	v_cvt_pk_bf16_f32 v40, v118, v90
	v_cvt_pk_bf16_f32 v41, v120, v92
	v_pk_mul_f32 v[60:61], v[60:61], v[134:135] op_sel_hi:[1,0]
	s_waitcnt lgkmcnt(7)
	v_mfma_f32_16x16x32_bf16 v[78:81], v[154:157], v[54:57], v[78:81]
	v_mul_f32_e64 v58, v58, v134
	v_mul_f32_e64 v59, v59, v134
	v_pk_mul_f32 v[52:53], v[64:65], v[134:135] op_sel_hi:[1,0]
	v_pk_mul_f32 v[50:51], v[62:63], v[134:135] op_sel_hi:[1,0]
	v_mfma_f32_16x16x32_bf16 v[66:69], v[154:157], v[38:41], v[66:69]
	v_cvt_pk_bf16_f32 v62, v123, v125
	s_waitcnt lgkmcnt(6)
	v_mfma_f32_16x16x32_bf16 v[74:77], v[158:161], v[54:57], v[74:77]
	v_cvt_pk_bf16_f32 v63, v127, v129
	v_cvt_pk_bf16_f32 v64, v131, v95
	v_cvt_pk_bf16_f32 v65, v133, v97
	v_mfma_f32_16x16x32_bf16 v[70:73], v[158:161], v[38:41], v[70:73]
	v_cvt_pk_bf16_f32 v46, v122, v124
	v_cvt_pk_bf16_f32 v47, v126, v128
	s_waitcnt lgkmcnt(5)
	v_mfma_f32_16x16x32_bf16 v[58:61], v[162:165], v[54:57], v[58:61]
	v_cvt_pk_bf16_f32 v48, v130, v94
	v_cvt_pk_bf16_f32 v49, v132, v96
	v_mov_b32_e32 v110, v152
	v_mfma_f32_16x16x32_bf16 v[42:45], v[162:165], v[38:41], v[42:45]
	v_mov_b32_e32 v111, v1
	s_waitcnt lgkmcnt(4)
	v_mfma_f32_16x16x32_bf16 v[86:89], v[166:169], v[54:57], v[50:53]
	v_mfma_f32_16x16x32_bf16 v[82:85], v[166:169], v[38:41], v[34:37]
	s_waitcnt lgkmcnt(2)
	v_mfma_f32_16x16x32_bf16 v[50:53], v[174:177], v[62:65], v[78:81]
	v_mfma_f32_16x16x32_bf16 v[34:37], v[174:177], v[46:49], v[66:69]
	s_waitcnt lgkmcnt(1)
	v_mfma_f32_16x16x32_bf16 v[58:61], v[178:181], v[62:65], v[58:61]
	v_mfma_f32_16x16x32_bf16 v[42:45], v[178:181], v[46:49], v[42:45]
	v_mfma_f32_16x16x32_bf16 v[54:57], v[170:173], v[62:65], v[74:77]
	v_mfma_f32_16x16x32_bf16 v[38:41], v[170:173], v[46:49], v[70:73]
	s_waitcnt lgkmcnt(0)
	v_mfma_f32_16x16x32_bf16 v[62:65], v[182:185], v[62:65], v[86:89]
	v_mfma_f32_16x16x32_bf16 v[46:49], v[182:185], v[46:49], v[82:85]
.LBB0_212:
	s_or_b64 exec, exec, s[80:81]
	s_add_i32 s34, s30, 1
	s_cmp_lt_u32 s34, 17
	s_cselect_b64 s[8:9], -1, 0
	s_cmp_gt_u32 s34, 16
	s_cbranch_scc1 .LBB0_214
	s_waitcnt vmcnt(2)
	ds_write_b128 v138, v[10:13] offset:16896
	ds_write_b64 v139, v[14:15] offset:33280
	ds_write_b64 v140, v[16:17] offset:33280

.LBB0_217:
	s_sub_i32 s8, s65, 63
	v_cmp_le_i32_e32 vcc, s8, v141
	s_and_b64 s[8:9], s[12:13], vcc
	s_and_saveexec_b64 s[80:81], s[8:9]
	s_cbranch_execz .LBB0_221
	ds_read_b128 v[66:69], v142 offset:256
	ds_read_b128 v[70:73], v142 offset:320
	ds_read_b128 v[74:77], v142 offset:384
	ds_read_b128 v[78:81], v142 offset:448
	ds_read_b128 v[154:157], v186 offset:16896
	ds_read_b128 v[158:161], v186 offset:18944
	ds_read_b128 v[162:165], v186 offset:20992
	ds_read_b128 v[166:169], v186 offset:23040
	ds_read_b128 v[170:173], v187 offset:16896
	ds_read_b128 v[174:177], v187 offset:18944
	ds_read_b128 v[178:181], v187 offset:20992
	ds_read_b128 v[182:185], v187 offset:23040
	v_cmp_gt_u32_e32 vcc, s65, v136
	s_waitcnt lgkmcnt(7)
	v_mfma_f32_16x16x32_bf16 v[86:89], v[154:157], v[30:33], v[66:69]
	v_mfma_f32_16x16x32_bf16 v[82:85], v[154:157], v[26:29], v[66:69]
	s_waitcnt lgkmcnt(6)
	v_mfma_f32_16x16x32_bf16 v[90:93], v[158:161], v[30:33], v[70:73]
	v_mfma_f32_16x16x32_bf16 v[70:73], v[158:161], v[26:29], v[70:73]
	s_waitcnt lgkmcnt(5)
	v_mfma_f32_16x16x32_bf16 v[94:97], v[162:165], v[30:33], v[74:77]
	v_mfma_f32_16x16x32_bf16 v[112:115], v[162:165], v[26:29], v[74:77]
	s_waitcnt lgkmcnt(4)
	v_mfma_f32_16x16x32_bf16 v[116:119], v[166:169], v[30:33], v[78:81]
	v_mfma_f32_16x16x32_bf16 v[78:81], v[166:169], v[26:29], v[78:81]
	s_waitcnt lgkmcnt(3)
	v_mfma_f32_16x16x32_bf16 v[66:69], v[170:173], v[22:25], v[86:89]
	v_mfma_f32_16x16x32_bf16 v[86:89], v[170:173], v[18:21], v[82:85]
	s_waitcnt lgkmcnt(2)
	v_mfma_f32_16x16x32_bf16 v[90:93], v[174:177], v[22:25], v[90:93]
	v_mfma_f32_16x16x32_bf16 v[74:77], v[174:177], v[18:21], v[70:73]
	s_waitcnt lgkmcnt(1)
	v_mfma_f32_16x16x32_bf16 v[82:85], v[178:181], v[22:25], v[94:97]
	v_mfma_f32_16x16x32_bf16 v[70:73], v[178:181], v[18:21], v[112:115]
	s_waitcnt lgkmcnt(0)
	v_mfma_f32_16x16x32_bf16 v[94:97], v[182:185], v[22:25], v[116:119]
	v_mfma_f32_16x16x32_bf16 v[78:81], v[182:185], v[18:21], v[78:81]
	s_and_saveexec_b64 s[82:83], vcc
	s_cbranch_execz .LBB0_220
	v_add_u32_e32 v1, s65, v137
	v_subrev_u32_e32 v113, 63, v1
	v_mov_b32_e32 v112, s41
	v_cmp_gt_i32_e32 vcc, v113, v148
	v_cmp_lt_i32_e64 s[8:9], v113, v148
	v_subrev_u32_e32 v114, 61, v1
	v_cndmask_b32_e32 v112, v66, v112, vcc
	v_cndmask_b32_e64 v66, v112, v66, s[8:9]
	v_cndmask_b32_e64 v67, v221, v67, s[8:9]
	v_cmp_le_i32_e64 s[8:9], v114, v148
	v_subrev_u32_e32 v115, 60, v1
	v_mov_b32_e32 v112, s41
	v_cndmask_b32_e64 v68, v221, v68, s[8:9]
	v_cmp_le_i32_e64 s[8:9], v115, v148
	v_subrev_u32_e32 v116, 28, v1
	s_nop 0
	v_cndmask_b32_e64 v69, v221, v69, s[8:9]
	v_cmp_gt_i32_e64 s[8:9], v113, v149
	s_nop 1
	v_cndmask_b32_e64 v112, v86, v112, s[8:9]
	v_cmp_lt_i32_e64 s[8:9], v113, v149
	v_subrev_u32_e32 v113, 47, v1
	s_nop 0
	v_cndmask_b32_e64 v86, v112, v86, s[8:9]
	v_cndmask_b32_e64 v87, v221, v87, s[8:9]
	v_cmp_le_i32_e64 s[8:9], v114, v149
	v_mov_b32_e32 v112, s41
	v_subrev_u32_e32 v114, 45, v1
	v_cndmask_b32_e64 v88, v221, v88, s[8:9]
	v_cmp_le_i32_e64 s[8:9], v115, v149
	v_cndmask_b32_e32 v74, v74, v112, vcc
	v_subrev_u32_e32 v115, 44, v1
	v_cndmask_b32_e64 v89, v221, v89, s[8:9]
	v_cmp_gt_i32_e64 s[8:9], v113, v148
	v_subrev_u32_e32 v113, 46, v1
	v_cmp_le_i32_e32 vcc, v113, v149
	v_cndmask_b32_e64 v90, v90, v112, s[8:9]
	v_cmp_le_i32_e64 s[8:9], v113, v148
	v_cndmask_b32_e32 v75, v221, v75, vcc
	v_cmp_le_i32_e32 vcc, v114, v149
	v_subrev_u32_e32 v113, 31, v1
	v_cndmask_b32_e64 v91, v221, v91, s[8:9]
	v_cndmask_b32_e32 v76, v221, v76, vcc
	v_cmp_le_i32_e32 vcc, v115, v149
	v_cmp_le_i32_e64 s[8:9], v114, v148
	v_subrev_u32_e32 v114, 30, v1
	v_cndmask_b32_e32 v77, v221, v77, vcc
	v_cmp_gt_i32_e32 vcc, v113, v148
	v_cndmask_b32_e64 v92, v221, v92, s[8:9]
	v_cmp_le_i32_e64 s[8:9], v115, v148
	v_cndmask_b32_e32 v82, v82, v112, vcc
	v_cmp_le_i32_e32 vcc, v114, v148
	v_subrev_u32_e32 v115, 29, v1
	v_cndmask_b32_e64 v93, v221, v93, s[8:9]
	v_cndmask_b32_e32 v83, v221, v83, vcc
	v_cmp_le_i32_e32 vcc, v115, v148
	s_nop 1
	v_cndmask_b32_e32 v84, v221, v84, vcc
	v_cmp_le_i32_e32 vcc, v116, v148
	s_nop 1
	v_cndmask_b32_e32 v85, v221, v85, vcc
	v_cmp_gt_i32_e32 vcc, v113, v149
	v_add_u32_e32 v113, -15, v1
	s_nop 0
	v_cndmask_b32_e32 v70, v70, v112, vcc
	v_cmp_le_i32_e32 vcc, v114, v149
	v_add_u32_e32 v114, -14, v1
	s_nop 0
	v_cndmask_b32_e32 v71, v221, v71, vcc
	v_cmp_le_i32_e32 vcc, v115, v149
	v_add_u32_e32 v115, -13, v1
	v_add_u32_e32 v1, -12, v1
	v_cndmask_b32_e32 v72, v221, v72, vcc
	v_cmp_le_i32_e32 vcc, v116, v149
	s_nop 1
	v_cndmask_b32_e32 v73, v221, v73, vcc
	v_cmp_gt_i32_e32 vcc, v113, v148
	s_nop 1
	v_cndmask_b32_e32 v94, v94, v112, vcc
	v_cmp_le_i32_e32 vcc, v114, v148
	s_nop 1
	v_cndmask_b32_e32 v95, v221, v95, vcc
	v_cmp_le_i32_e32 vcc, v115, v148
	s_nop 1
	v_cndmask_b32_e32 v96, v221, v96, vcc
	v_cmp_le_i32_e32 vcc, v1, v148
	s_nop 1
	v_cndmask_b32_e32 v97, v221, v97, vcc
	v_cmp_gt_i32_e32 vcc, v113, v149
	s_nop 1
	v_cndmask_b32_e32 v78, v78, v112, vcc
	v_cmp_le_i32_e32 vcc, v114, v149
	s_nop 1
	v_cndmask_b32_e32 v79, v221, v79, vcc
	v_cmp_le_i32_e32 vcc, v115, v149
	s_nop 1
	v_cndmask_b32_e32 v80, v221, v80, vcc
	v_cmp_le_i32_e32 vcc, v1, v149
	s_nop 1
	v_cndmask_b32_e32 v81, v221, v81, vcc
.LBB0_220:
	s_or_b64 exec, exec, s[82:83]
	v_max_f32_e32 v1, v68, v69
	v_max_f32_e32 v112, v92, v93
	v_max3_f32 v1, v66, v67, v1
	v_max3_f32 v112, v90, v91, v112
	v_max3_f32 v1, v1, s41, v112
	v_max_f32_e32 v112, v84, v85
	v_max_f32_e32 v114, v96, v96
	v_max_f32_e32 v113, v114, v97
	v_max3_f32 v112, v82, v83, v112
	v_max3_f32 v113, v94, v95, v113
	v_max3_f32 v1, v1, v112, v113
	ds_bpermute_b32 v112, v135, v1
	s_waitcnt lgkmcnt(0)
	v_max_f32_e32 v1, v1, v112
	ds_bpermute_b32 v112, v101, v1
	s_waitcnt lgkmcnt(0)
	v_max3_f32 v1, v111, v1, v112
	v_sub_f32_e32 v66, v66, v1
	v_sub_f32_e32 v112, v111, v1
	v_exp_f32_e32 v111, v66
	v_sub_f32_e32 v66, v67, v1
	v_exp_f32_e32 v113, v66
	v_sub_f32_e32 v66, v68, v1
	v_exp_f32_e32 v115, v66
	v_sub_f32_e32 v66, v69, v1
	v_exp_f32_e32 v117, v66
	v_sub_f32_e32 v66, v90, v1
	v_exp_f32_e32 v119, v66
	v_sub_f32_e32 v66, v91, v1
	v_exp_f32_e32 v91, v66
	v_sub_f32_e32 v66, v92, v1
	v_exp_f32_e32 v121, v66
	v_sub_f32_e32 v66, v93, v1
	v_exp_f32_e32 v93, v66
	v_sub_f32_e32 v66, v82, v1
	v_exp_f32_e32 v123, v66
	v_sub_f32_e32 v66, v83, v1
	v_exp_f32_e32 v125, v66
	v_sub_f32_e32 v66, v84, v1
	v_exp_f32_e32 v127, v66
	v_sub_f32_e32 v66, v85, v1
	v_exp_f32_e32 v129, v66
	v_sub_f32_e32 v66, v94, v1
	v_max_f32_e32 v90, v88, v89
	v_max_f32_e32 v92, v76, v77
	v_max3_f32 v90, v86, v87, v90
	v_max3_f32 v92, v74, v75, v92
	v_exp_f32_e32 v131, v66
	v_sub_f32_e32 v66, v95, v1
	v_max3_f32 v90, v90, s41, v92
	v_exp_f32_e32 v95, v66
	v_sub_f32_e32 v66, v96, v1
	v_max_f32_e32 v92, v72, v73
	v_max_f32_e32 v94, v80, v81
	v_max3_f32 v92, v70, v71, v92
	v_max3_f32 v94, v78, v79, v94
	v_max3_f32 v90, v90, v92, v94
	ds_bpermute_b32 v92, v135, v90
	v_exp_f32_e32 v152, v112
	v_exp_f32_e32 v133, v66
	v_sub_f32_e32 v66, v97, v1
	v_exp_f32_e32 v97, v66
	s_waitcnt lgkmcnt(0)
	v_max_f32_e32 v90, v90, v92
	ds_bpermute_b32 v92, v101, v90
	v_pk_mul_f32 v[84:85], v[52:53], v[152:153] op_sel_hi:[1,0]
	v_pk_mul_f32 v[82:83], v[50:51], v[152:153] op_sel_hi:[1,0]
	v_pk_mul_f32 v[68:69], v[56:57], v[152:153] op_sel_hi:[1,0]
	v_pk_mul_f32 v[66:67], v[54:55], v[152:153] op_sel_hi:[1,0]
	s_waitcnt lgkmcnt(0)
	v_max3_f32 v134, v110, v90, v92
	v_sub_f32_e32 v86, v86, v134
	v_pk_mul_f32 v[60:61], v[60:61], v[152:153] op_sel_hi:[1,0]
	v_pk_mul_f32 v[58:59], v[58:59], v[152:153] op_sel_hi:[1,0]
	v_pk_mul_f32 v[52:53], v[64:65], v[152:153] op_sel_hi:[1,0]
	v_pk_mul_f32 v[50:51], v[62:63], v[152:153] op_sel_hi:[1,0]
	v_sub_f32_e32 v153, v110, v134
	v_exp_f32_e32 v110, v86
	v_sub_f32_e32 v86, v87, v134
	v_exp_f32_e32 v112, v86
	v_sub_f32_e32 v86, v88, v134
	v_sub_f32_e32 v74, v74, v134
	v_exp_f32_e32 v114, v86
	v_sub_f32_e32 v86, v89, v134
	v_exp_f32_e32 v118, v74
	v_sub_f32_e32 v74, v75, v134
	v_exp_f32_e32 v116, v86
	v_exp_f32_e32 v90, v74
	v_sub_f32_e32 v74, v76, v134
	v_sub_f32_e32 v70, v70, v134
	v_exp_f32_e32 v120, v74
	v_pk_add_f32 v[74:75], v[110:111], 0 op_sel_hi:[1,0]
	v_exp_f32_e32 v122, v70
	v_sub_f32_e32 v70, v71, v134
	v_pk_add_f32 v[74:75], v[112:113], v[74:75]
	v_exp_f32_e32 v124, v70
	v_sub_f32_e32 v70, v72, v134
	v_pk_add_f32 v[74:75], v[114:115], v[74:75]
	v_sub_f32_e32 v76, v77, v134
	v_exp_f32_e32 v126, v70
	v_sub_f32_e32 v70, v73, v134
	v_pk_add_f32 v[74:75], v[116:117], v[74:75]
	v_exp_f32_e32 v92, v76
	v_exp_f32_e32 v128, v70
	v_sub_f32_e32 v70, v78, v134
	v_pk_add_f32 v[74:75], v[118:119], v[74:75]
	v_exp_f32_e32 v130, v70
	v_sub_f32_e32 v70, v79, v134
	v_pk_add_f32 v[74:75], v[90:91], v[74:75]
	v_exp_f32_e32 v94, v70
	v_sub_f32_e32 v70, v80, v134
	v_pk_add_f32 v[74:75], v[120:121], v[74:75]
	v_exp_f32_e32 v132, v70
	v_sub_f32_e32 v70, v81, v134
	v_exp_f32_e32 v96, v70
	v_pk_add_f32 v[70:71], v[92:93], v[74:75]
	v_exp_f32_e32 v78, v153
	v_pk_add_f32 v[70:71], v[122:123], v[70:71]
	v_mov_b32_e32 v79, v152
	v_pk_add_f32 v[70:71], v[124:125], v[70:71]
	v_pk_add_f32 v[70:71], v[126:127], v[70:71]
	v_pk_mul_f32 v[76:77], v[36:37], v[78:79] op_sel_hi:[1,0]
	v_pk_add_f32 v[70:71], v[128:129], v[70:71]
	v_pk_mul_f32 v[74:75], v[34:35], v[78:79] op_sel_hi:[1,0]
	v_pk_add_f32 v[70:71], v[130:131], v[70:71]
	v_pk_mul_f32 v[72:73], v[40:41], v[78:79] op_sel_hi:[1,0]
	v_pk_add_f32 v[70:71], v[94:95], v[70:71]
	v_pk_mul_f32 v[44:45], v[44:45], v[78:79] op_sel_hi:[1,0]
	v_pk_add_f32 v[70:71], v[132:133], v[70:71]
	v_pk_mul_f32 v[42:43], v[42:43], v[78:79] op_sel_hi:[1,0]
	v_pk_add_f32 v[70:71], v[96:97], v[70:71]
	v_pk_mul_f32 v[36:37], v[48:49], v[78:79] op_sel_hi:[1,0]
	v_pk_fma_f32 v[104:105], v[104:105], v[78:79], v[70:71]
	v_pk_mul_f32 v[70:71], v[38:39], v[78:79] op_sel_hi:[1,0]
	v_pk_mul_f32 v[34:35], v[46:47], v[78:79] op_sel_hi:[1,0]
	ds_read_b128 v[154:157], v188 offset:33280
	ds_read_b128 v[158:161], v188 offset:35328
	ds_read_b128 v[162:165], v188 offset:37376
	ds_read_b128 v[166:169], v188 offset:39424
	ds_read_b128 v[170:173], v189 offset:35328
	ds_read_b128 v[174:177], v189 offset:33280
	ds_read_b128 v[178:181], v189 offset:37376
	ds_read_b128 v[182:185], v189 offset:39424
	v_cvt_pk_bf16_f32 v54, v111, v113
	v_cvt_pk_bf16_f32 v55, v115, v117
	v_cvt_pk_bf16_f32 v56, v119, v91
	v_cvt_pk_bf16_f32 v57, v121, v93
	v_cvt_pk_bf16_f32 v38, v110, v112
	v_cvt_pk_bf16_f32 v39, v114, v116
	v_cvt_pk_bf16_f32 v40, v118, v90
	v_cvt_pk_bf16_f32 v41, v120, v92
	s_waitcnt lgkmcnt(7)
	v_mfma_f32_16x16x32_bf16 v[82:85], v[154:157], v[54:57], v[82:85]
	v_cvt_pk_bf16_f32 v62, v123, v125
	v_cvt_pk_bf16_f32 v63, v127, v129
	v_cvt_pk_bf16_f32 v64, v131, v95
	v_mfma_f32_16x16x32_bf16 v[74:77], v[154:157], v[38:41], v[74:77]
	v_cvt_pk_bf16_f32 v65, v133, v97
	v_cvt_pk_bf16_f32 v46, v122, v124
	s_waitcnt lgkmcnt(6)
	v_mfma_f32_16x16x32_bf16 v[66:69], v[158:161], v[54:57], v[66:69]
	v_cvt_pk_bf16_f32 v47, v126, v128
	v_cvt_pk_bf16_f32 v48, v130, v94
	v_cvt_pk_bf16_f32 v49, v132, v96
	v_mfma_f32_16x16x32_bf16 v[70:73], v[158:161], v[38:41], v[70:73]
	v_mov_b32_e32 v110, v134
	v_mov_b32_e32 v111, v1
	s_waitcnt lgkmcnt(5)
	v_mfma_f32_16x16x32_bf16 v[58:61], v[162:165], v[54:57], v[58:61]
	v_mfma_f32_16x16x32_bf16 v[42:45], v[162:165], v[38:41], v[42:45]
	s_waitcnt lgkmcnt(4)
	v_mfma_f32_16x16x32_bf16 v[86:89], v[166:169], v[54:57], v[50:53]
	v_mfma_f32_16x16x32_bf16 v[78:81], v[166:169], v[38:41], v[34:37]
	s_waitcnt lgkmcnt(3)
	v_mfma_f32_16x16x32_bf16 v[54:57], v[170:173], v[62:65], v[66:69]
	s_waitcnt lgkmcnt(1)
	v_mfma_f32_16x16x32_bf16 v[58:61], v[178:181], v[62:65], v[58:61]
	v_mfma_f32_16x16x32_bf16 v[42:45], v[178:181], v[46:49], v[42:45]
	v_mfma_f32_16x16x32_bf16 v[50:53], v[174:177], v[62:65], v[82:85]
	v_mfma_f32_16x16x32_bf16 v[34:37], v[174:177], v[46:49], v[74:77]
	v_mfma_f32_16x16x32_bf16 v[38:41], v[170:173], v[46:49], v[70:73]
	s_waitcnt lgkmcnt(0)
	v_mfma_f32_16x16x32_bf16 v[62:65], v[182:185], v[62:65], v[86:89]
	v_mfma_f32_16x16x32_bf16 v[46:49], v[182:185], v[46:49], v[78:81]
.LBB0_221:
	s_or_b64 exec, exec, s[80:81]
	s_andn2_b64 vcc, exec, s[78:79]
	s_cbranch_vccnz .LBB0_204
	s_waitcnt vmcnt(2)
	ds_write_b128 v138, v[2:5] offset:8704
	ds_write_b64 v139, v[6:7] offset:25088
	ds_write_b64 v140, v[8:9] offset:25088
	s_branch .LBB0_204

.LBB0_277:
	v_add_u32_e32 v109, s65, v86
	v_cmp_lt_i32_e32 vcc, 2, v109
	v_mov_b32_e32 v92, 0
	v_mov_b32_e32 v94, 0
	v_mov_b32_e32 v95, 0
	v_mov_b32_e32 v96, 0
	v_mov_b32_e32 v97, 0
	v_mov_b32_e32 v98, 0
	v_mov_b32_e32 v99, 0
	v_mov_b32_e32 v100, 0
	v_mov_b32_e32 v101, 0
	s_and_saveexec_b64 s[16:17], vcc
	s_cbranch_execz .LBB0_279
	v_lshlrev_b32_e32 v94, 16, v52
	v_and_b32_e32 v95, 0xffff0000, v52
	v_lshlrev_b32_e32 v96, 16, v53
	v_and_b32_e32 v97, 0xffff0000, v53
	v_lshlrev_b32_e32 v98, 16, v54
	v_and_b32_e32 v99, 0xffff0000, v54
	v_lshlrev_b32_e32 v100, 16, v55
	v_and_b32_e32 v101, 0xffff0000, v55
.LBB0_279:
	s_or_b64 exec, exec, s[16:17]
	v_cmp_lt_i32_e32 vcc, 1, v109
	v_mov_b32_e32 v93, 0
	v_mov_b32_e32 v102, 0
	v_mov_b32_e32 v103, 0
	v_mov_b32_e32 v104, 0
	v_mov_b32_e32 v105, 0
	v_mov_b32_e32 v106, 0
	v_mov_b32_e32 v107, 0
	s_and_saveexec_b64 s[16:17], vcc
	s_cbranch_execz .LBB0_281
	v_lshlrev_b32_e32 v92, 16, v56
	v_and_b32_e32 v93, 0xffff0000, v56
	v_lshlrev_b32_e32 v102, 16, v57
	v_and_b32_e32 v103, 0xffff0000, v57
	v_lshlrev_b32_e32 v104, 16, v58
	v_and_b32_e32 v105, 0xffff0000, v58
	v_lshlrev_b32_e32 v106, 16, v59
	v_and_b32_e32 v107, 0xffff0000, v59
.LBB0_281:
	s_or_b64 exec, exec, s[16:17]
	v_cmp_lt_i32_e32 vcc, 0, v109
	v_mov_b32_e32 v108, 0
	v_mov_b32_e32 v110, 0
	v_mov_b32_e32 v111, 0
	v_mov_b32_e32 v112, 0
	v_mov_b32_e32 v113, 0
	v_mov_b32_e32 v114, 0
	v_mov_b32_e32 v115, 0
	v_mov_b32_e32 v116, 0
	v_mov_b32_e32 v117, 0
	s_and_saveexec_b64 s[16:17], vcc
	s_cbranch_execz .LBB0_283
	v_lshlrev_b32_e32 v110, 16, v60
	v_and_b32_e32 v111, 0xffff0000, v60
	v_lshlrev_b32_e32 v112, 16, v61
	v_and_b32_e32 v113, 0xffff0000, v61
	v_lshlrev_b32_e32 v114, 16, v62
	v_and_b32_e32 v115, 0xffff0000, v62
	v_lshlrev_b32_e32 v116, 16, v63
	v_and_b32_e32 v117, 0xffff0000, v63
.LBB0_283:
	s_or_b64 exec, exec, s[16:17]
	v_cmp_lt_i32_e32 vcc, -1, v109
	v_mov_b32_e32 v109, 0
	v_mov_b32_e32 v122, 0
	v_mov_b32_e32 v123, 0
	v_mov_b32_e32 v120, 0
	v_mov_b32_e32 v121, 0
	v_mov_b32_e32 v118, 0
	v_mov_b32_e32 v119, 0
	s_and_saveexec_b64 s[16:17], vcc
	s_cbranch_execz .LBB0_285
	v_lshlrev_b32_e32 v108, 16, v64
	v_and_b32_e32 v109, 0xffff0000, v64
	v_lshlrev_b32_e32 v122, 16, v65
	v_and_b32_e32 v123, 0xffff0000, v65
	v_lshlrev_b32_e32 v120, 16, v66
	v_and_b32_e32 v121, 0xffff0000, v66
	v_lshlrev_b32_e32 v118, 16, v67
	v_and_b32_e32 v119, 0xffff0000, v67
.LBB0_285:
	s_or_b64 exec, exec, s[16:17]
	v_pk_fma_f32 v[94:95], v[24:25], v[94:95], v[16:17]
	v_pk_fma_f32 v[96:97], v[26:27], v[96:97], v[18:19]
	v_pk_fma_f32 v[98:99], v[20:21], v[98:99], v[12:13]
	v_pk_fma_f32 v[100:101], v[22:23], v[100:101], v[14:15]
	v_pk_fma_f32 v[92:93], v[28:29], v[92:93], v[94:95]
	v_pk_fma_f32 v[94:95], v[30:31], v[102:103], v[96:97]
	v_pk_fma_f32 v[96:97], v[32:33], v[104:105], v[98:99]
	v_pk_fma_f32 v[98:99], v[34:35], v[106:107], v[100:101]
	v_pk_fma_f32 v[92:93], v[36:37], v[110:111], v[92:93]
	v_pk_fma_f32 v[94:95], v[38:39], v[112:113], v[94:95]
	v_pk_fma_f32 v[100:101], v[40:41], v[114:115], v[96:97]
	v_pk_fma_f32 v[102:103], v[42:43], v[116:117], v[98:99]
	v_pk_fma_f32 v[92:93], v[44:45], v[108:109], v[92:93]
	v_pk_fma_f32 v[94:95], v[46:47], v[122:123], v[94:95]
	v_cvt_pk_bf16_f32 v96, v92, v93
	v_pk_fma_f32 v[100:101], v[48:49], v[120:121], v[100:101]
	v_cvt_pk_bf16_f32 v97, v94, v95
	v_pk_fma_f32 v[102:103], v[50:51], v[118:119], v[102:103]
	v_cvt_pk_bf16_f32 v98, v100, v101
	s_nop 0
	v_cvt_pk_bf16_f32 v99, v102, v103
	ds_write_b128 v137, v[96:99]
	ds_write_b128 v138, v[92:95] offset:9216
	ds_write_b128 v138, v[100:103] offset:9232
	s_waitcnt lgkmcnt(0)
	s_barrier
	ds_read_b128 v[92:95], v139
	ds_read_b128 v[96:99], v139 offset:64
	s_waitcnt lgkmcnt(1)
	v_mfma_f32_16x16x32_bf16 v[92:95], v[92:95], v[4:7], 0
	s_waitcnt lgkmcnt(0)
	v_mfma_f32_16x16x32_bf16 v[92:95], v[96:99], v[8:11], v[92:95]
	s_nop 7
	v_add_f32_e32 v92, v124, v92
	v_mul_f32_e32 v92, 0xbfb8aa3b, v92
	v_exp_f32_e32 v92, v92
	v_add_f32_e32 v93, v124, v93
	v_mul_f32_e32 v93, 0xbfb8aa3b, v93
	v_exp_f32_e32 v93, v93
	v_add_f32_e32 v92, 1.0, v92
	v_div_scale_f32 v96, s[16:17], v92, v92, 1.0
	v_rcp_f32_e32 v97, v96
	v_add_f32_e32 v93, 1.0, v93
	v_add_f32_e32 v94, v124, v94
	v_mul_f32_e32 v94, 0xbfb8aa3b, v94
	v_fma_f32 v98, -v96, v97, 1.0
	v_fmac_f32_e32 v97, v98, v97
	v_div_scale_f32 v98, vcc, 1.0, v92, 1.0
	v_mul_f32_e32 v99, v98, v97
	v_fma_f32 v100, -v96, v99, v98
	v_fmac_f32_e32 v99, v100, v97
	v_fma_f32 v96, -v96, v99, v98
	v_div_fmas_f32 v96, v96, v97, v99
	v_div_scale_f32 v97, s[16:17], v93, v93, 1.0
	v_rcp_f32_e32 v98, v97
	v_div_fixup_f32 v92, v96, v92, 1.0
	v_mul_f32_e32 v96, v1, v92
	v_cndmask_b32_e64 v92, v92, v96, s[6:7]
	v_fma_f32 v96, -v97, v98, 1.0
	v_fmac_f32_e32 v98, v96, v98
	v_div_scale_f32 v96, vcc, 1.0, v93, 1.0
	v_mul_f32_e32 v99, v96, v98
	v_exp_f32_e32 v94, v94
	v_fma_f32 v100, -v97, v99, v96
	v_fmac_f32_e32 v99, v100, v98
	v_fma_f32 v96, -v97, v99, v96
	v_div_fmas_f32 v96, v96, v98, v99
	v_add_f32_e32 v94, 1.0, v94
	v_div_fixup_f32 v93, v96, v93, 1.0
	v_div_scale_f32 v96, s[16:17], v94, v94, 1.0
	v_rcp_f32_e32 v97, v96
	v_mul_f32_e32 v98, v1, v93
	v_cndmask_b32_e64 v93, v93, v98, s[6:7]
	ds_write2st64_b32 v140, v92, v93 offset1:1
	v_fma_f32 v92, -v96, v97, 1.0
	v_add_f32_e32 v95, v124, v95
	v_fmac_f32_e32 v97, v92, v97
	v_div_scale_f32 v92, vcc, 1.0, v94, 1.0
	v_mul_f32_e32 v95, 0xbfb8aa3b, v95
	v_mul_f32_e32 v93, v92, v97
	v_exp_f32_e32 v95, v95
	v_fma_f32 v98, -v96, v93, v92
	v_fmac_f32_e32 v93, v98, v97
	v_fma_f32 v92, -v96, v93, v92
	v_div_fmas_f32 v92, v92, v97, v93
	v_add_f32_e32 v93, 1.0, v95
	v_div_scale_f32 v95, s[16:17], v93, v93, 1.0
	v_rcp_f32_e32 v96, v95
	v_div_fixup_f32 v92, v92, v94, 1.0
	v_mul_f32_e32 v94, v1, v92
	v_cndmask_b32_e64 v92, v92, v94, s[6:7]
	v_fma_f32 v94, -v95, v96, 1.0
	v_fmac_f32_e32 v96, v94, v96
	v_div_scale_f32 v94, vcc, 1.0, v93, 1.0
	v_mul_f32_e32 v97, v94, v96
	v_fma_f32 v98, -v95, v97, v94
	v_fmac_f32_e32 v97, v98, v96
	v_fma_f32 v94, -v95, v97, v94
	v_div_fmas_f32 v94, v94, v96, v97
	v_div_fixup_f32 v93, v94, v93, 1.0
	v_mul_f32_e32 v94, v1, v93
	v_cndmask_b32_e64 v93, v93, v94, s[6:7]
	ds_write2st64_b32 v140, v92, v93 offset0:2 offset1:3
	ds_read_b128 v[92:95], v139 offset:2304
	ds_read_b128 v[96:99], v139 offset:2368
	s_waitcnt lgkmcnt(1)
	v_mfma_f32_16x16x32_bf16 v[92:95], v[92:95], v[4:7], 0
	s_waitcnt lgkmcnt(0)
	v_mfma_f32_16x16x32_bf16 v[92:95], v[96:99], v[8:11], v[92:95]
	s_nop 7
	v_add_f32_e32 v92, v124, v92
	v_mul_f32_e32 v92, 0xbfb8aa3b, v92
	v_exp_f32_e32 v92, v92
	v_add_f32_e32 v93, v124, v93
	v_mul_f32_e32 v93, 0xbfb8aa3b, v93
	v_exp_f32_e32 v93, v93
	v_add_f32_e32 v92, 1.0, v92
	v_div_scale_f32 v96, s[16:17], v92, v92, 1.0
	v_rcp_f32_e32 v97, v96
	v_add_f32_e32 v93, 1.0, v93
	v_add_f32_e32 v94, v124, v94
	v_mul_f32_e32 v94, 0xbfb8aa3b, v94
	v_fma_f32 v98, -v96, v97, 1.0
	v_fmac_f32_e32 v97, v98, v97
	v_div_scale_f32 v98, vcc, 1.0, v92, 1.0
	v_mul_f32_e32 v99, v98, v97
	v_fma_f32 v100, -v96, v99, v98
	v_fmac_f32_e32 v99, v100, v97
	v_fma_f32 v96, -v96, v99, v98
	v_div_fmas_f32 v96, v96, v97, v99
	v_div_scale_f32 v97, s[16:17], v93, v93, 1.0
	v_rcp_f32_e32 v98, v97
	v_div_fixup_f32 v92, v96, v92, 1.0
	v_mul_f32_e32 v96, v1, v92
	v_cndmask_b32_e64 v92, v92, v96, s[6:7]
	v_fma_f32 v96, -v97, v98, 1.0
	v_fmac_f32_e32 v98, v96, v98
	v_div_scale_f32 v96, vcc, 1.0, v93, 1.0
	v_mul_f32_e32 v99, v96, v98
	v_exp_f32_e32 v94, v94
	v_fma_f32 v100, -v97, v99, v96
	v_fmac_f32_e32 v99, v100, v98
	v_fma_f32 v96, -v97, v99, v96
	v_div_fmas_f32 v96, v96, v98, v99
	v_add_f32_e32 v94, 1.0, v94
	v_div_fixup_f32 v93, v96, v93, 1.0
	v_div_scale_f32 v96, s[16:17], v94, v94, 1.0
	v_rcp_f32_e32 v97, v96
	v_mul_f32_e32 v98, v1, v93
	v_cndmask_b32_e64 v93, v93, v98, s[6:7]
	ds_write2st64_b32 v140, v92, v93 offset0:16 offset1:17
	v_fma_f32 v92, -v96, v97, 1.0
	v_add_f32_e32 v95, v124, v95
	v_fmac_f32_e32 v97, v92, v97
	v_div_scale_f32 v92, vcc, 1.0, v94, 1.0
	v_mul_f32_e32 v95, 0xbfb8aa3b, v95
	v_mul_f32_e32 v93, v92, v97
	v_exp_f32_e32 v95, v95
	v_fma_f32 v98, -v96, v93, v92
	v_fmac_f32_e32 v93, v98, v97
	v_fma_f32 v92, -v96, v93, v92
	v_div_fmas_f32 v92, v92, v97, v93
	v_add_f32_e32 v93, 1.0, v95
	v_div_scale_f32 v95, s[16:17], v93, v93, 1.0
	v_rcp_f32_e32 v96, v95
	v_div_fixup_f32 v92, v92, v94, 1.0
	v_mul_f32_e32 v94, v1, v92
	v_cndmask_b32_e64 v92, v92, v94, s[6:7]
	v_fma_f32 v94, -v95, v96, 1.0
	v_fmac_f32_e32 v96, v94, v96
	v_div_scale_f32 v94, vcc, 1.0, v93, 1.0
	v_mul_f32_e32 v97, v94, v96
	v_fma_f32 v98, -v95, v97, v94
	v_fmac_f32_e32 v97, v98, v96
	v_fma_f32 v94, -v95, v97, v94
	v_div_fmas_f32 v94, v94, v96, v97
	v_div_fixup_f32 v93, v94, v93, 1.0
	v_mul_f32_e32 v94, v1, v93
	v_cndmask_b32_e64 v93, v93, v94, s[6:7]
	ds_write2st64_b32 v140, v92, v93 offset0:18 offset1:19
	ds_read_b128 v[92:95], v139 offset:4608
	ds_read_b128 v[96:99], v139 offset:4672
	s_waitcnt lgkmcnt(1)
	v_mfma_f32_16x16x32_bf16 v[92:95], v[92:95], v[4:7], 0
	s_waitcnt lgkmcnt(0)
	v_mfma_f32_16x16x32_bf16 v[92:95], v[96:99], v[8:11], v[92:95]
	s_nop 7
	v_add_f32_e32 v92, v124, v92
	v_mul_f32_e32 v92, 0xbfb8aa3b, v92
	v_exp_f32_e32 v92, v92
	v_add_f32_e32 v93, v124, v93
	v_mul_f32_e32 v93, 0xbfb8aa3b, v93
	v_exp_f32_e32 v93, v93
	v_add_f32_e32 v92, 1.0, v92
	v_div_scale_f32 v96, s[16:17], v92, v92, 1.0
	v_rcp_f32_e32 v97, v96
	v_add_f32_e32 v93, 1.0, v93
	v_add_f32_e32 v94, v124, v94
	v_mul_f32_e32 v94, 0xbfb8aa3b, v94
	v_fma_f32 v98, -v96, v97, 1.0
	v_fmac_f32_e32 v97, v98, v97
	v_div_scale_f32 v98, vcc, 1.0, v92, 1.0
	v_mul_f32_e32 v99, v98, v97
	v_fma_f32 v100, -v96, v99, v98
	v_fmac_f32_e32 v99, v100, v97
	v_fma_f32 v96, -v96, v99, v98
	v_div_fmas_f32 v96, v96, v97, v99
	v_div_scale_f32 v97, s[16:17], v93, v93, 1.0
	v_rcp_f32_e32 v98, v97
	v_div_fixup_f32 v92, v96, v92, 1.0
	v_mul_f32_e32 v96, v1, v92
	v_cndmask_b32_e64 v92, v92, v96, s[6:7]
	v_fma_f32 v96, -v97, v98, 1.0
	v_fmac_f32_e32 v98, v96, v98
	v_div_scale_f32 v96, vcc, 1.0, v93, 1.0
	v_mul_f32_e32 v99, v96, v98
	v_exp_f32_e32 v94, v94
	v_fma_f32 v100, -v97, v99, v96
	v_fmac_f32_e32 v99, v100, v98
	v_fma_f32 v96, -v97, v99, v96
	v_div_fmas_f32 v96, v96, v98, v99
	v_add_f32_e32 v94, 1.0, v94
	v_div_fixup_f32 v93, v96, v93, 1.0
	v_div_scale_f32 v96, s[16:17], v94, v94, 1.0
	v_rcp_f32_e32 v97, v96
	v_mul_f32_e32 v98, v1, v93
	v_cndmask_b32_e64 v93, v93, v98, s[6:7]
	ds_write2st64_b32 v140, v92, v93 offset0:32 offset1:33
	v_fma_f32 v92, -v96, v97, 1.0
	v_add_f32_e32 v95, v124, v95
	v_fmac_f32_e32 v97, v92, v97
	v_div_scale_f32 v92, vcc, 1.0, v94, 1.0
	v_mul_f32_e32 v95, 0xbfb8aa3b, v95
	v_mul_f32_e32 v93, v92, v97
	v_exp_f32_e32 v95, v95
	v_fma_f32 v98, -v96, v93, v92
	v_fmac_f32_e32 v93, v98, v97
	v_fma_f32 v92, -v96, v93, v92
	v_div_fmas_f32 v92, v92, v97, v93
	v_add_f32_e32 v93, 1.0, v95
	v_div_scale_f32 v95, s[16:17], v93, v93, 1.0
	v_rcp_f32_e32 v96, v95
	v_div_fixup_f32 v92, v92, v94, 1.0
	v_mul_f32_e32 v94, v1, v92
	v_cndmask_b32_e64 v92, v92, v94, s[6:7]
	v_fma_f32 v94, -v95, v96, 1.0
	v_fmac_f32_e32 v96, v94, v96
	v_div_scale_f32 v94, vcc, 1.0, v93, 1.0
	v_mul_f32_e32 v97, v94, v96
	v_fma_f32 v98, -v95, v97, v94
	v_fmac_f32_e32 v97, v98, v96
	v_fma_f32 v94, -v95, v97, v94
	v_div_fmas_f32 v94, v94, v96, v97
	v_div_fixup_f32 v93, v94, v93, 1.0
	v_mul_f32_e32 v94, v1, v93
	v_cndmask_b32_e64 v93, v93, v94, s[6:7]
	ds_write2st64_b32 v140, v92, v93 offset0:34 offset1:35
	ds_read_b128 v[92:95], v139 offset:6912
	ds_read_b128 v[96:99], v139 offset:6976
	s_waitcnt lgkmcnt(1)
	v_mfma_f32_16x16x32_bf16 v[92:95], v[92:95], v[4:7], 0
	s_waitcnt lgkmcnt(0)
	v_mfma_f32_16x16x32_bf16 v[92:95], v[96:99], v[8:11], v[92:95]
	s_nop 7
	v_add_f32_e32 v92, v124, v92
	v_mul_f32_e32 v92, 0xbfb8aa3b, v92
	v_exp_f32_e32 v92, v92
	v_add_f32_e32 v93, v124, v93
	v_mul_f32_e32 v93, 0xbfb8aa3b, v93
	v_exp_f32_e32 v93, v93
	v_add_f32_e32 v92, 1.0, v92
	v_div_scale_f32 v96, s[16:17], v92, v92, 1.0
	v_rcp_f32_e32 v97, v96
	v_add_f32_e32 v93, 1.0, v93
	v_add_f32_e32 v94, v124, v94
	v_mul_f32_e32 v94, 0xbfb8aa3b, v94
	v_fma_f32 v98, -v96, v97, 1.0
	v_fmac_f32_e32 v97, v98, v97
	v_div_scale_f32 v98, vcc, 1.0, v92, 1.0
	v_mul_f32_e32 v99, v98, v97
	v_fma_f32 v100, -v96, v99, v98
	v_fmac_f32_e32 v99, v100, v97
	v_fma_f32 v96, -v96, v99, v98
	v_div_fmas_f32 v96, v96, v97, v99
	v_div_scale_f32 v97, s[16:17], v93, v93, 1.0
	v_rcp_f32_e32 v98, v97
	v_div_fixup_f32 v92, v96, v92, 1.0
	v_mul_f32_e32 v96, v1, v92
	v_cndmask_b32_e64 v92, v92, v96, s[6:7]
	v_fma_f32 v96, -v97, v98, 1.0
	v_fmac_f32_e32 v98, v96, v98
	v_div_scale_f32 v96, vcc, 1.0, v93, 1.0
	v_mul_f32_e32 v99, v96, v98
	v_exp_f32_e32 v94, v94
	v_fma_f32 v100, -v97, v99, v96
	v_fmac_f32_e32 v99, v100, v98
	v_fma_f32 v96, -v97, v99, v96
	v_div_fmas_f32 v96, v96, v98, v99
	v_add_f32_e32 v94, 1.0, v94
	v_div_fixup_f32 v93, v96, v93, 1.0
	v_div_scale_f32 v96, s[16:17], v94, v94, 1.0
	v_rcp_f32_e32 v97, v96
	v_mul_f32_e32 v98, v1, v93
	v_cndmask_b32_e64 v93, v93, v98, s[6:7]
	ds_write2st64_b32 v140, v92, v93 offset0:48 offset1:49
	v_fma_f32 v92, -v96, v97, 1.0
	v_add_f32_e32 v95, v124, v95
	v_fmac_f32_e32 v97, v92, v97
	v_div_scale_f32 v92, vcc, 1.0, v94, 1.0
	v_mul_f32_e32 v95, 0xbfb8aa3b, v95
	v_mul_f32_e32 v93, v92, v97
	v_exp_f32_e32 v95, v95
	v_fma_f32 v98, -v96, v93, v92
	v_fmac_f32_e32 v93, v98, v97
	v_fma_f32 v92, -v96, v93, v92
	v_div_fmas_f32 v92, v92, v97, v93
	v_add_f32_e32 v93, 1.0, v95
	v_div_scale_f32 v95, s[16:17], v93, v93, 1.0
	v_rcp_f32_e32 v96, v95
	v_div_fixup_f32 v92, v92, v94, 1.0
	v_mul_f32_e32 v94, v1, v92
	v_cndmask_b32_e64 v92, v92, v94, s[6:7]
	v_fma_f32 v94, -v95, v96, 1.0
	v_fmac_f32_e32 v96, v94, v96
	v_div_scale_f32 v94, vcc, 1.0, v93, 1.0
	v_mul_f32_e32 v97, v94, v96
	v_fma_f32 v98, -v95, v97, v94
	v_fmac_f32_e32 v97, v98, v96
	v_fma_f32 v94, -v95, v97, v94
	v_div_fmas_f32 v94, v94, v96, v97
	v_div_fixup_f32 v93, v94, v93, 1.0
	v_mul_f32_e32 v94, v1, v93
	v_cndmask_b32_e64 v93, v93, v94, s[6:7]
	ds_write2st64_b32 v140, v92, v93 offset0:50 offset1:51
	s_waitcnt lgkmcnt(0)
	s_barrier
	ds_read2st64_b32 v[94:95], v135 offset0:100 offset1:101
	ds_read2st64_b32 v[96:97], v135 offset0:102 offset1:103
	ds_read2st64_b32 v[104:105], v135 offset0:104 offset1:105
	ds_read2st64_b32 v[106:107], v135 offset0:106 offset1:107
	s_and_b32 s16, s65, 64
	s_waitcnt lgkmcnt(3)
	v_add_f32_e32 v93, v94, v94
	v_mul_f32_e32 v92, 0x3fb8aa3b, v94
	v_fmamk_f32 v94, v93, 0x39500d01, v210
	v_fmaak_f32 v94, v93, v94, 0x3c088889
	v_exp_f32_e32 v92, v92
	v_fmaak_f32 v94, v93, v94, 0x3d2aaaab
	v_fmaak_f32 v94, v93, v94, 0x3e2aaaab
	v_fma_f32 v94, v93, v94, 0.5
	v_fma_f32 v94, v93, v94, 1.0
	v_mul_f32_e64 v94, v94, -v93
	v_fma_f32 v98, -v92, v92, 1.0
	v_cmp_lt_f32_e32 vcc, s29, v93
	s_nop 1
	v_cndmask_b32_e32 v93, v98, v94, vcc
	ds_read2st64_b32 v[98:99], v135 offset0:36 offset1:37
	ds_read2st64_b32 v[100:101], v135 offset0:164 offset1:165
	ds_read2st64_b32 v[102:103], v135 offset0:166 offset1:167
	ds_read2st64_b32 v[108:109], v135 offset0:168 offset1:169
	ds_read2st64_b32 v[110:111], v135 offset0:170 offset1:171
	ds_read2st64_b32 v[112:113], v135 offset0:38 offset1:39
	ds_read2st64_b32 v[114:115], v135 offset0:40 offset1:41
	ds_read2st64_b32 v[116:117], v135 offset0:42 offset1:43
	s_waitcnt lgkmcnt(6)
	v_mul_f32_e32 v94, v100, v98
	v_mul_f32_e32 v98, 0x3fb8aa3b, v95
	v_add_f32_e32 v95, v95, v95
	v_fmamk_f32 v100, v95, 0x39500d01, v210
	v_fmaak_f32 v100, v95, v100, 0x3c088889
	v_exp_f32_e32 v98, v98
	v_fmaak_f32 v100, v95, v100, 0x3d2aaaab
	v_fmaak_f32 v100, v95, v100, 0x3e2aaaab
	v_sqrt_f32_e32 v93, v93
	v_fma_f32 v100, v95, v100, 0.5
	v_fma_f32 v100, v95, v100, 1.0
	v_mul_f32_e64 v100, v100, -v95
	v_fma_f32 v118, -v98, v98, 1.0
	v_cmp_lt_f32_e32 vcc, s29, v95
	s_nop 1
	v_cndmask_b32_e32 v95, v118, v100, vcc
	v_sqrt_f32_e32 v100, v95
	v_mul_f32_e32 v95, v94, v93
	v_mul_f32_e32 v94, 0x3fb8aa3b, v96
	v_mul_f32_e32 v93, v101, v99
	v_exp_f32_e32 v99, v94
	v_add_f32_e32 v94, v96, v96
	v_fmamk_f32 v96, v94, 0x39500d01, v210
	v_fmaak_f32 v96, v94, v96, 0x3c088889
	v_fmaak_f32 v96, v94, v96, 0x3d2aaaab
	v_fmaak_f32 v96, v94, v96, 0x3e2aaaab
	v_fma_f32 v96, v94, v96, 0.5
	v_fma_f32 v96, v94, v96, 1.0
	v_mul_f32_e32 v93, v93, v100
	v_mul_f32_e64 v96, v96, -v94
	v_fma_f32 v100, -v99, v99, 1.0
	v_cmp_lt_f32_e32 vcc, s29, v94
	v_fmac_f32_e32 v95, 0, v92
	v_fmac_f32_e32 v93, v98, v95
	v_cndmask_b32_e32 v94, v100, v96, vcc
	v_sqrt_f32_e32 v94, v94
	s_waitcnt lgkmcnt(2)
	v_mul_f32_e32 v96, v102, v112
	v_mul_f32_e32 v98, v92, v98
	v_mul_f32_e32 v94, v96, v94
	v_mul_f32_e32 v96, 0x3fb8aa3b, v97
	v_exp_f32_e32 v100, v96
	v_add_f32_e32 v96, v97, v97
	v_fmamk_f32 v97, v96, 0x39500d01, v210
	v_fmaak_f32 v97, v96, v97, 0x3c088889
	v_fmaak_f32 v97, v96, v97, 0x3d2aaaab
	v_fmaak_f32 v97, v96, v97, 0x3e2aaaab
	v_fma_f32 v97, v96, v97, 0.5
	v_fma_f32 v97, v96, v97, 1.0
	v_mul_f32_e64 v97, v97, -v96
	v_fma_f32 v101, -v100, v100, 1.0
	v_cmp_lt_f32_e32 vcc, s29, v96
	v_fmac_f32_e32 v94, v99, v93
	s_nop 0
	v_cndmask_b32_e32 v96, v101, v97, vcc
	v_sqrt_f32_e32 v96, v96
	v_mul_f32_e32 v97, v103, v113
	v_mul_f32_e32 v101, v98, v99
	v_mul_f32_e32 v96, v97, v96
	v_mul_f32_e32 v97, 0x3fb8aa3b, v104
	v_exp_f32_e32 v99, v97
	v_add_f32_e32 v97, v104, v104
	v_fmamk_f32 v102, v97, 0x39500d01, v210
	v_fmaak_f32 v102, v97, v102, 0x3c088889
	v_fmaak_f32 v102, v97, v102, 0x3d2aaaab
	v_fmaak_f32 v102, v97, v102, 0x3e2aaaab
	v_fma_f32 v102, v97, v102, 0.5
	v_fma_f32 v102, v97, v102, 1.0
	v_mul_f32_e64 v102, v102, -v97
	v_fma_f32 v103, -v99, v99, 1.0
	v_cmp_lt_f32_e32 vcc, s29, v97
	v_fmac_f32_e32 v96, v100, v94
	s_nop 0
	v_cndmask_b32_e32 v97, v103, v102, vcc
	v_sqrt_f32_e32 v97, v97
	v_add_f32_e32 v102, v105, v105
	v_mul_f32_e32 v103, v101, v100
	s_waitcnt lgkmcnt(1)
	v_mul_f32_e32 v100, v108, v114
	v_fmamk_f32 v104, v102, 0x39500d01, v210
	v_mul_f32_e32 v97, v100, v97
	v_mul_f32_e32 v100, 0x3fb8aa3b, v105
	v_fmaak_f32 v104, v102, v104, 0x3c088889
	v_exp_f32_e32 v100, v100
	v_fmaak_f32 v104, v102, v104, 0x3d2aaaab
	v_fmaak_f32 v104, v102, v104, 0x3e2aaaab
	v_fma_f32 v104, v102, v104, 0.5
	v_fma_f32 v104, v102, v104, 1.0
	v_mul_f32_e64 v104, v104, -v102
	v_fma_f32 v105, -v100, v100, 1.0
	v_cmp_lt_f32_e32 vcc, s29, v102
	v_fmac_f32_e32 v97, v99, v96
	s_nop 0
	v_cndmask_b32_e32 v102, v105, v104, vcc
	v_sqrt_f32_e32 v102, v102
	v_mul_f32_e32 v104, v103, v99
	v_mul_f32_e32 v99, v109, v115
	v_mul_f32_e32 v99, v99, v102
	v_mul_f32_e32 v102, 0x3fb8aa3b, v106
	v_exp_f32_e32 v108, v102
	v_add_f32_e32 v102, v106, v106
	v_fmamk_f32 v105, v102, 0x39500d01, v210
	v_fmaak_f32 v105, v102, v105, 0x3c088889
	v_fmaak_f32 v105, v102, v105, 0x3d2aaaab
	v_fmaak_f32 v105, v102, v105, 0x3e2aaaab
	v_fma_f32 v105, v102, v105, 0.5
	v_fma_f32 v105, v102, v105, 1.0
	v_mul_f32_e64 v105, v105, -v102
	v_fma_f32 v106, -v108, v108, 1.0
	v_cmp_lt_f32_e32 vcc, s29, v102
	v_fmac_f32_e32 v99, v100, v97
	s_nop 0
	v_cndmask_b32_e32 v102, v106, v105, vcc
	v_sqrt_f32_e32 v102, v102
	v_mul_f32_e32 v105, v104, v100
	s_waitcnt lgkmcnt(0)
	v_mul_f32_e32 v100, v110, v116
	v_mul_f32_e32 v102, v100, v102
	v_mul_f32_e32 v100, 0x3fb8aa3b, v107
	v_exp_f32_e32 v106, v100
	v_add_f32_e32 v100, v107, v107
	v_fmamk_f32 v107, v100, 0x39500d01, v210
	v_fmaak_f32 v107, v100, v107, 0x3c088889
	v_fmaak_f32 v107, v100, v107, 0x3d2aaaab
	v_fmaak_f32 v107, v100, v107, 0x3e2aaaab
	v_fma_f32 v107, v100, v107, 0.5
	v_fma_f32 v107, v100, v107, 1.0
	v_mul_f32_e64 v107, v107, -v100
	v_fma_f32 v109, -v106, v106, 1.0
	v_cmp_lt_f32_e32 vcc, s29, v100
	v_fmac_f32_e32 v102, v108, v99
	s_nop 0
	v_cndmask_b32_e32 v100, v109, v107, vcc
	v_sqrt_f32_e32 v100, v100
	v_mul_f32_e32 v107, v105, v108
	v_mul_f32_e32 v108, v111, v117
	v_mul_f32_e32 v100, v108, v100
	v_fmac_f32_e32 v100, v106, v102
	v_mul_f32_e32 v106, v107, v106
	v_lshl_add_u32 v108, s16, 2, v132
	ds_write2st64_b32 v125, v106, v100 offset0:228 offset1:236
	s_waitcnt lgkmcnt(0)
	s_barrier
	ds_read_b32 v108, v108 offset:62464
	s_and_saveexec_b64 s[16:17], s[8:9]
	s_cbranch_execz .LBB0_289
	s_mov_b64 s[78:79], 0
	v_mov_b32_e32 v109, v136
	v_mov_b32_e32 v110, v85
